# attnC main loop software-pipelined: PV of previous key tile interleaved with softmax of current tile; S accumulators seeded from a constant -Mb block; V staging moved after the barrier
# speedup vs baseline: 1.0628x; 1.0108x over previous
.LBB0_1086:
	s_lshl_b64 s[58:59], s[8:9], 10
	s_lshl_b64 s[64:65], s[8:9], 11
	v_mov_b32_e32 v245, v151
	s_lshl_b32 s8, s68, 7
	v_lshl_add_u64 v[0:1], s[62:63], 0, v[244:245]
	v_mov_b32_e32 v165, v151
	v_mov_b32_e32 v247, v151
	s_add_u32 s70, s62, s8
	v_lshl_add_u64 v[0:1], v[0:1], 0, v[164:165]
	v_lshl_add_u64 v[2:3], s[62:63], 0, v[246:247]
	s_addc_u32 s71, s63, 0
	v_lshl_add_u64 v[2:3], v[2:3], 0, v[164:165]
	global_load_dwordx4 v[32:35], v[0:1], off
	global_load_dwordx4 v[36:39], v[2:3], off
	v_lshl_add_u64 v[0:1], s[70:71], 0, v[244:245]
	v_lshl_add_u64 v[0:1], v[0:1], 0, v[164:165]
	v_lshl_add_u64 v[2:3], s[70:71], 0, v[246:247]
	v_lshl_add_u64 v[2:3], v[2:3], 0, v[164:165]
	global_load_dwordx4 v[40:43], v[0:1], off
	global_load_dwordx4 v[44:47], v[2:3], off
	v_accvgpr_read_b32 v0, a209
	v_mul_u32_u24_e32 v0, s68, v0
	v_lshlrev_b32_e32 v64, 1, v0
	v_mov_b32_e32 v65, v151
	v_mul_u32_u24_e32 v2, s68, v154
	v_lshl_add_u64 v[0:1], s[60:61], 0, v[64:65]
	v_lshlrev_b32_e32 v66, 1, v2
	v_mov_b32_e32 v67, v151
	v_lshl_add_u64 v[0:1], v[0:1], 0, v[164:165]
	v_lshl_add_u64 v[2:3], s[60:61], 0, v[66:67]
	v_lshl_add_u64 v[2:3], v[2:3], 0, v[164:165]
	global_load_dwordx4 v[48:51], v[0:1], off
	global_load_dwordx4 v[52:55], v[2:3], off
	v_mul_u32_u24_e32 v0, s68, v155
	v_lshlrev_b32_e32 v68, 1, v0
	v_mov_b32_e32 v69, v151
	v_mul_u32_u24_e32 v2, s68, v162
	v_lshl_add_u64 v[0:1], s[60:61], 0, v[68:69]
	v_lshlrev_b32_e32 v70, 1, v2
	v_mov_b32_e32 v71, v151
	v_lshl_add_u64 v[0:1], v[0:1], 0, v[164:165]
	v_lshl_add_u64 v[2:3], s[60:61], 0, v[70:71]
	v_lshl_add_u64 v[2:3], v[2:3], 0, v[164:165]
	global_load_dwordx4 v[56:59], v[0:1], off
	global_load_dwordx4 v[60:63], v[2:3], off
	v_mov_b32_e32 v251, v151
	v_lshl_add_u64 v[0:1], v[168:169], 0, s[64:65]
	v_lshl_add_u64 v[2:3], v[0:1], 0, v[150:151]
	v_lshl_add_u64 v[0:1], v[0:1], 0, v[250:251]
	global_load_dwordx4 v[28:31], v[2:3], off
	global_load_dwordx4 v[24:27], v[2:3], off offset:32
	global_load_dwordx4 v[20:23], v[2:3], off offset:64
	global_load_dwordx4 v[16:19], v[2:3], off offset:96
	global_load_dwordx4 v[12:15], v[0:1], off
	global_load_dwordx4 v[8:11], v[0:1], off offset:32
	global_load_dwordx4 v[4:7], v[0:1], off offset:64
	s_nop 0
	global_load_dwordx4 v[0:3], v[0:1], off offset:96
	v_lshl_add_u64 v[82:83], s[62:63], 0, v[170:171]
	v_lshl_add_u64 v[84:85], s[62:63], 0, v[242:243]
	v_lshl_add_u64 v[86:87], v[82:83], 0, s[8:9]
	v_lshl_add_u64 v[88:89], v[84:85], 0, s[8:9]
	s_add_i32 s8, s67, 1
	s_add_u32 s60, s60, 0x80
	v_mov_b32_e32 v80, 0
	s_addc_u32 s61, s61, 0
	v_accvgpr_write_b32 a31, 0
	v_accvgpr_write_b32 a30, 0
	v_accvgpr_write_b32 a29, 0
	v_accvgpr_write_b32 a28, 0
	v_accvgpr_write_b32 a27, 0
	v_accvgpr_write_b32 a26, 0
	v_accvgpr_write_b32 a25, 0
	v_accvgpr_write_b32 a24, 0
	v_accvgpr_write_b32 a23, 0
	v_accvgpr_write_b32 a22, 0
	v_lshl_add_u64 v[90:91], s[60:61], 0, v[64:65]
	v_lshl_add_u64 v[92:93], s[60:61], 0, v[66:67]
	v_lshl_add_u64 v[94:95], s[60:61], 0, v[68:69]
	v_lshl_add_u64 v[96:97], s[60:61], 0, v[70:71]
	v_accvgpr_write_b32 a21, 0
	v_accvgpr_write_b32 a20, 0
	v_accvgpr_write_b32 a19, 0
	v_accvgpr_write_b32 a18, 0
	v_accvgpr_write_b32 a17, 0
	v_accvgpr_write_b32 a16, 0
	v_accvgpr_write_b32 a111, 0
	v_accvgpr_write_b32 a110, 0
	v_accvgpr_write_b32 a109, 0
	v_accvgpr_write_b32 a108, 0
	v_accvgpr_write_b32 a107, 0
	v_accvgpr_write_b32 a106, 0
	v_accvgpr_write_b32 a105, 0
	v_accvgpr_write_b32 a104, 0
	v_accvgpr_write_b32 a103, 0
	v_accvgpr_write_b32 a102, 0
	v_accvgpr_write_b32 a101, 0
	v_accvgpr_write_b32 a100, 0
	v_accvgpr_write_b32 a99, 0
	v_accvgpr_write_b32 a98, 0
	v_accvgpr_write_b32 a97, 0
	v_accvgpr_write_b32 a96, 0
	v_accvgpr_write_b32 a143, 0
	v_accvgpr_write_b32 a142, 0
	v_accvgpr_write_b32 a141, 0
	v_accvgpr_write_b32 a140, 0
	v_accvgpr_write_b32 a139, 0
	v_accvgpr_write_b32 a138, 0
	v_accvgpr_write_b32 a137, 0
	v_accvgpr_write_b32 a136, 0
	v_accvgpr_write_b32 a135, 0
	v_accvgpr_write_b32 a134, 0
	v_accvgpr_write_b32 a133, 0
	v_accvgpr_write_b32 a132, 0
	v_accvgpr_write_b32 a131, 0
	v_accvgpr_write_b32 a130, 0
	v_accvgpr_write_b32 a129, 0
	v_accvgpr_write_b32 a128, 0
	v_accvgpr_write_b32 a63, 0
	v_accvgpr_write_b32 a62, 0
	v_accvgpr_write_b32 a61, 0
	v_accvgpr_write_b32 a60, 0
	v_accvgpr_write_b32 a59, 0
	v_accvgpr_write_b32 a58, 0
	v_accvgpr_write_b32 a57, 0
	v_accvgpr_write_b32 a56, 0
	v_accvgpr_write_b32 a55, 0
	v_accvgpr_write_b32 a54, 0
	v_accvgpr_write_b32 a53, 0
	v_accvgpr_write_b32 a52, 0
	v_accvgpr_write_b32 a51, 0
	v_accvgpr_write_b32 a50, 0
	v_accvgpr_write_b32 a49, 0
	v_accvgpr_write_b32 a48, 0
	v_accvgpr_write_b32 a95, 0
	v_accvgpr_write_b32 a94, 0
	v_accvgpr_write_b32 a93, 0
	v_accvgpr_write_b32 a92, 0
	v_accvgpr_write_b32 a91, 0
	v_accvgpr_write_b32 a90, 0
	v_accvgpr_write_b32 a89, 0
	v_accvgpr_write_b32 a88, 0
	v_accvgpr_write_b32 a87, 0
	v_accvgpr_write_b32 a86, 0
	v_accvgpr_write_b32 a85, 0
	v_accvgpr_write_b32 a84, 0
	v_accvgpr_write_b32 a83, 0
	v_accvgpr_write_b32 a82, 0
	v_accvgpr_write_b32 a81, 0
	v_accvgpr_write_b32 a80, 0
	v_accvgpr_write_b32 a47, 0
	v_accvgpr_write_b32 a46, 0
	v_accvgpr_write_b32 a45, 0
	v_accvgpr_write_b32 a44, 0
	v_accvgpr_write_b32 a43, 0
	v_accvgpr_write_b32 a42, 0
	v_accvgpr_write_b32 a41, 0
	v_accvgpr_write_b32 a40, 0
	v_accvgpr_write_b32 a39, 0
	v_accvgpr_write_b32 a38, 0
	v_accvgpr_write_b32 a37, 0
	v_accvgpr_write_b32 a36, 0
	v_accvgpr_write_b32 a35, 0
	v_accvgpr_write_b32 a34, 0
	v_accvgpr_write_b32 a33, 0
	v_accvgpr_write_b32 a32, 0
	v_accvgpr_write_b32 a127, 0
	v_accvgpr_write_b32 a126, 0
	v_accvgpr_write_b32 a125, 0
	v_accvgpr_write_b32 a124, 0
	v_accvgpr_write_b32 a123, 0
	v_accvgpr_write_b32 a122, 0
	v_accvgpr_write_b32 a121, 0
	v_accvgpr_write_b32 a120, 0
	v_accvgpr_write_b32 a119, 0
	v_accvgpr_write_b32 a118, 0
	v_accvgpr_write_b32 a117, 0
	v_accvgpr_write_b32 a116, 0
	v_accvgpr_write_b32 a115, 0
	v_accvgpr_write_b32 a114, 0
	v_accvgpr_write_b32 a113, 0
	v_accvgpr_write_b32 a112, 0
	v_accvgpr_write_b32 a79, 0
	v_accvgpr_write_b32 a78, 0
	v_accvgpr_write_b32 a77, 0
	v_accvgpr_write_b32 a76, 0
	v_accvgpr_write_b32 a75, 0
	v_accvgpr_write_b32 a74, 0
	v_accvgpr_write_b32 a73, 0
	v_accvgpr_write_b32 a72, 0
	v_accvgpr_write_b32 a71, 0
	v_accvgpr_write_b32 a70, 0
	v_accvgpr_write_b32 a69, 0
	v_accvgpr_write_b32 a68, 0
	v_accvgpr_write_b32 a67, 0
	v_accvgpr_write_b32 a66, 0
	v_accvgpr_write_b32 a65, 0
	v_accvgpr_write_b32 a64, 0
	s_mov_b32 s60, 0
	v_mov_b32_e32 v81, v80
	s_waitcnt vmcnt(15)
	ds_write_b128 v129, v[32:35]
	s_waitcnt vmcnt(14)
	ds_write_b128 v135, v[36:39]
	s_waitcnt vmcnt(13)
	ds_write_b128 v129, v[40:43] offset:9216
	s_waitcnt vmcnt(12)
	ds_write_b128 v135, v[44:47] offset:9216
	s_waitcnt vmcnt(11)
	ds_write_b128 v129, v[48:51] offset:36864
	s_waitcnt vmcnt(10)
	ds_write_b128 v135, v[52:55] offset:36864
	s_waitcnt vmcnt(9)
	ds_write_b128 v163, v[56:59] offset:36864
	s_waitcnt vmcnt(8)
	ds_write_b128 v166, v[60:63] offset:36864
	v_accvgpr_write_b32 a160, 0
	v_mov_b32_e32 v48, 0
	v_accvgpr_write_b32 a161, 0
	v_mov_b32_e32 v49, 0
	v_accvgpr_write_b32 a162, 0
	v_mov_b32_e32 v50, 0
	v_accvgpr_write_b32 a163, 0
	v_mov_b32_e32 v51, 0
	v_accvgpr_write_b32 a164, 0
	v_mov_b32_e32 v52, 0
	v_accvgpr_write_b32 a165, 0
	v_mov_b32_e32 v53, 0
	v_accvgpr_write_b32 a166, 0
	v_mov_b32_e32 v54, 0
	v_accvgpr_write_b32 a167, 0
	v_mov_b32_e32 v55, 0
	v_accvgpr_write_b32 a168, 0
	v_mov_b32_e32 v56, 0
	v_accvgpr_write_b32 a169, 0
	v_mov_b32_e32 v57, 0
	v_accvgpr_write_b32 a170, 0
	v_mov_b32_e32 v58, 0
	v_accvgpr_write_b32 a171, 0
	v_mov_b32_e32 v59, 0
	v_accvgpr_write_b32 a172, 0
	v_mov_b32_e32 v60, 0
	v_accvgpr_write_b32 a173, 0
	v_mov_b32_e32 v61, 0
	v_accvgpr_write_b32 a174, 0
	v_mov_b32_e32 v62, 0
	v_accvgpr_write_b32 a175, 0
	v_mov_b32_e32 v63, 0
	v_accvgpr_write_b32 a176, 0
	v_mov_b32_e32 v116, 0
	v_accvgpr_write_b32 a177, 0
	v_mov_b32_e32 v117, 0
	v_accvgpr_write_b32 a178, 0
	v_mov_b32_e32 v118, 0
	v_accvgpr_write_b32 a179, 0
	v_mov_b32_e32 v119, 0
	v_accvgpr_write_b32 a180, 0
	v_mov_b32_e32 v120, 0
	v_accvgpr_write_b32 a181, 0
	v_mov_b32_e32 v121, 0
	v_accvgpr_write_b32 a182, 0
	v_mov_b32_e32 v122, 0
	v_accvgpr_write_b32 a183, 0
	v_mov_b32_e32 v123, 0
	v_accvgpr_write_b32 a184, 0
	v_mov_b32_e32 v124, 0
	v_accvgpr_write_b32 a185, 0
	v_mov_b32_e32 v125, 0
	v_accvgpr_write_b32 a186, 0
	v_mov_b32_e32 v126, 0
	v_accvgpr_write_b32 a187, 0
	v_mov_b32_e32 v127, 0
	v_accvgpr_write_b32 a188, 0
	v_mov_b32_e32 v130, 0
	v_accvgpr_write_b32 a189, 0
	v_mov_b32_e32 v131, 0
	v_accvgpr_write_b32 a190, 0
	v_mov_b32_e32 v132, 0
	v_accvgpr_write_b32 a191, 0
	v_mov_b32_e32 v133, 0
	v_accvgpr_read_b32 v32, a0
	v_accvgpr_read_b32 v33, a0
	v_accvgpr_read_b32 v34, a0
	v_accvgpr_read_b32 v35, a0
	v_accvgpr_read_b32 v36, a0
	v_accvgpr_read_b32 v37, a0
	v_accvgpr_read_b32 v38, a0
	v_accvgpr_read_b32 v39, a0
	v_accvgpr_read_b32 v40, a0
	v_accvgpr_read_b32 v41, a0
	v_accvgpr_read_b32 v42, a0
	v_accvgpr_read_b32 v43, a0
	v_accvgpr_read_b32 v44, a0
	v_accvgpr_read_b32 v45, a0
	v_accvgpr_read_b32 v46, a0
	v_accvgpr_read_b32 v47, a0
	v_mbcnt_lo_u32_b32 v235, -1, 0
	v_mbcnt_hi_u32_b32 v235, -1, v235
	v_lshlrev_b32_e32 v235, 4, v235
	v_add_u32_e32 v235, 0xd800, v235
	s_waitcnt lgkmcnt(0)
	ds_write_b128 v235, a[160:163]
	ds_write_b128 v235, a[160:163] offset:1024
	ds_write_b128 v235, a[160:163] offset:2048
	ds_write_b128 v235, a[160:163] offset:3072
	ds_write_b128 v235, a[160:163] offset:4096
	ds_write_b128 v235, a[160:163] offset:5120
	ds_write_b128 v235, a[160:163] offset:6144
	ds_write_b128 v235, a[160:163] offset:7168
	ds_write_b128 v235, a[160:163] offset:8192
	s_waitcnt lgkmcnt(0)
	ds_write_b128 v235, a[160:163] offset:9216
	ds_write_b128 v235, a[160:163] offset:10240
	ds_write_b128 v235, a[160:163] offset:11264
	ds_write_b128 v235, a[160:163] offset:12288
	ds_write_b128 v235, a[160:163] offset:13312
	ds_write_b128 v235, a[160:163] offset:14336
	ds_write_b128 v235, a[160:163] offset:15360
	ds_write_b128 v235, a[160:163] offset:16384
	ds_write_b128 v235, a[160:163] offset:17408
.LBB0_1087:
	s_and_b32 s61, s60, 1
	s_xor_b32 s62, s61, 1
	s_mulk_i32 s61, 0x4800
	s_mulk_i32 s62, 0x4800
	v_add_u32_e32 v233, s61, v128
	v_add_u32_e32 v234, s62, v152
	s_waitcnt vmcnt(0) lgkmcnt(0)
	s_barrier
	ds_read_b128 a[144:147], v233
	ds_read_b128 a[148:151], v233 offset:32
	ds_read_b128 a[152:155], v233 offset:64
	ds_read_b128 a[156:159], v233 offset:96
	s_waitcnt lgkmcnt(3)
	v_mfma_f32_32x32x16_bf16 v[188:203], a[144:147], v[28:31], v[32:47]
	s_cmp_eq_u32 s60, 0
	s_cselect_b32 s32, 0x9000, s61
	v_add3_u32 v224, s32, v153, v134
	v_add3_u32 v230, s32, v158, v134
	v_mfma_f32_32x32x16_bf16 v[172:187], a[144:147], v[12:15], v[32:47]
	v_add3_u32 v231, s32, v159, v134
	v_add3_u32 v232, s32, v160, v134
	ds_write_b128 v224, v[140:143] offset:36864
	ds_read_b128 a[144:147], v233 offset:4608
	s_waitcnt lgkmcnt(4)
	v_mfma_f32_32x32x16_bf16 v[188:203], a[148:151], v[24:27], v[188:203]
	ds_write_b128 v230, v[144:147] offset:36864
	ds_write_b128 v231, v[220:223] offset:36864
	ds_write_b128 v232, v[226:229] offset:36864
	v_lshl_add_u64 v[98:99], v[82:83], 0, v[156:157]
	v_mfma_f32_32x32x16_bf16 v[172:187], a[148:151], v[8:11], v[172:187]
	global_load_dwordx4 v[64:67], v[98:99], off
	v_lshl_add_u64 v[98:99], v[84:85], 0, v[156:157]
	global_load_dwordx4 v[68:71], v[98:99], off
	ds_read_b128 a[148:151], v233 offset:4640
	s_waitcnt lgkmcnt(7)
	v_mfma_f32_32x32x16_bf16 v[188:203], a[152:155], v[20:23], v[188:203]
	v_lshl_add_u64 v[98:99], v[86:87], 0, v[156:157]
	global_load_dwordx4 v[72:75], v[98:99], off
	v_lshl_add_u64 v[98:99], v[88:89], 0, v[156:157]
	v_mfma_f32_32x32x16_bf16 v[172:187], a[152:155], v[4:7], v[172:187]
	global_load_dwordx4 v[76:79], v[98:99], off
	v_accvgpr_write_b32 a160, v48
	v_accvgpr_write_b32 a161, v49
	v_accvgpr_write_b32 a162, v50
	ds_read_b128 a[152:155], v233 offset:4672
	s_waitcnt lgkmcnt(7)
	v_mfma_f32_32x32x16_bf16 v[188:203], a[156:159], v[16:19], v[188:203]
	v_accvgpr_write_b32 a163, v51
	v_accvgpr_write_b32 a164, v52
	v_accvgpr_write_b32 a165, v53
	v_mfma_f32_32x32x16_bf16 v[172:187], a[156:159], v[0:3], v[172:187]
	v_accvgpr_write_b32 a166, v54
	v_accvgpr_write_b32 a167, v55
	v_accvgpr_write_b32 a168, v56
	ds_read_b128 a[156:159], v233 offset:4704
	s_waitcnt lgkmcnt(6)
	v_mfma_f32_32x32x16_bf16 v[204:219], a[144:147], v[28:31], v[32:47]
	v_accvgpr_write_b32 a169, v57
	v_accvgpr_write_b32 a170, v58
	v_accvgpr_write_b32 a171, v59
	v_accvgpr_write_b32 a172, v60
	v_mfma_f32_32x32x16_bf16 v[100:115], a[144:147], v[12:15], v[32:47]
	v_accvgpr_write_b32 a173, v61
	v_accvgpr_write_b32 a174, v62
	v_accvgpr_write_b32 a175, v63
	s_waitcnt lgkmcnt(2)
	v_mfma_f32_32x32x16_bf16 v[204:219], a[148:151], v[24:27], v[204:219]
	v_accvgpr_write_b32 a176, v116
	v_accvgpr_write_b32 a177, v117
	v_accvgpr_write_b32 a178, v118
	v_accvgpr_write_b32 a179, v119
	v_mfma_f32_32x32x16_bf16 v[100:115], a[148:151], v[8:11], v[100:115]
	v_accvgpr_write_b32 a180, v120
	v_accvgpr_write_b32 a181, v121
	v_accvgpr_write_b32 a182, v122
	s_waitcnt lgkmcnt(1)
	v_mfma_f32_32x32x16_bf16 v[204:219], a[152:155], v[20:23], v[204:219]
	v_accvgpr_write_b32 a183, v123
	v_accvgpr_write_b32 a184, v124
	v_accvgpr_write_b32 a185, v125
	v_mfma_f32_32x32x16_bf16 v[100:115], a[152:155], v[4:7], v[100:115]
	v_accvgpr_write_b32 a186, v126
	v_accvgpr_write_b32 a187, v127
	v_accvgpr_write_b32 a188, v130
	v_accvgpr_write_b32 a189, v131
	s_waitcnt lgkmcnt(0)
	v_mfma_f32_32x32x16_bf16 v[204:219], a[156:159], v[16:19], v[204:219]
	v_accvgpr_write_b32 a190, v132
	v_accvgpr_write_b32 a191, v133
	v_lshl_add_u64 v[82:83], v[82:83], 0, s[54:55]
	v_mfma_f32_32x32x16_bf16 v[100:115], a[156:159], v[0:3], v[100:115]
	v_lshl_add_u64 v[84:85], v[84:85], 0, s[54:55]
	v_lshl_add_u64 v[86:87], v[86:87], 0, s[54:55]
	v_lshl_add_u64 v[88:89], v[88:89], 0, s[54:55]
	ds_read_b128 a[144:147], v234 offset:36864
	ds_read_b128 a[148:151], v234 offset:36896
	ds_read_b128 a[152:155], v234 offset:36928
	ds_read_b128 a[156:159], v234 offset:36960
	s_waitcnt lgkmcnt(3)
	v_mfma_f32_32x32x16_bf16 a[128:143], a[144:147], a[160:163], a[128:143]
	v_exp_f32_e32 v188, v188
	v_exp_f32_e32 v189, v189
	v_exp_f32_e32 v190, v190
	v_mfma_f32_32x32x16_bf16 a[112:127], a[144:147], a[176:179], a[112:127]
	v_exp_f32_e32 v191, v191
	v_exp_f32_e32 v192, v192
	v_exp_f32_e32 v193, v193
	v_exp_f32_e32 v194, v194
	ds_read_b128 a[144:147], v234 offset:41472
	s_waitcnt lgkmcnt(3)
	v_mfma_f32_32x32x16_bf16 a[128:143], a[148:151], a[164:167], a[128:143]
	v_exp_f32_e32 v195, v195
	v_exp_f32_e32 v196, v196
	v_exp_f32_e32 v197, v197
	v_exp_f32_e32 v198, v198
	v_mfma_f32_32x32x16_bf16 a[112:127], a[148:151], a[180:183], a[112:127]
	v_exp_f32_e32 v199, v199
	v_exp_f32_e32 v200, v200
	v_exp_f32_e32 v201, v201
	v_exp_f32_e32 v202, v202
	ds_read_b128 a[148:151], v234 offset:41504
	s_waitcnt lgkmcnt(3)
	v_mfma_f32_32x32x16_bf16 a[128:143], a[152:155], a[168:171], a[128:143]
	v_exp_f32_e32 v203, v203
	v_pk_add_f32 v[136:137], v[188:189], v[190:191]
	v_pk_add_f32 v[136:137], v[136:137], v[192:193]
	v_pk_add_f32 v[136:137], v[136:137], v[194:195]
	v_mfma_f32_32x32x16_bf16 a[112:127], a[152:155], a[184:187], a[112:127]
	v_pk_add_f32 v[136:137], v[136:137], v[196:197]
	v_pk_add_f32 v[136:137], v[136:137], v[198:199]
	v_pk_add_f32 v[136:137], v[136:137], v[200:201]
	v_pk_add_f32 v[136:137], v[136:137], v[202:203]
	ds_read_b128 a[152:155], v234 offset:41536
	s_waitcnt lgkmcnt(3)
	v_mfma_f32_32x32x16_bf16 a[128:143], a[156:159], a[172:175], a[128:143]
	v_cvt_pk_bf16_f32 v48, v188, v189
	v_cvt_pk_bf16_f32 v49, v190, v191
	v_cvt_pk_bf16_f32 v50, v192, v193
	v_cvt_pk_bf16_f32 v51, v194, v195
	v_cvt_pk_bf16_f32 v52, v196, v197
	v_cvt_pk_bf16_f32 v53, v198, v199
	v_cvt_pk_bf16_f32 v54, v200, v201
	v_mfma_f32_32x32x16_bf16 a[112:127], a[156:159], a[188:191], a[112:127]
	v_cvt_pk_bf16_f32 v55, v202, v203
	v_add3_u32 v224, s62, v153, v134
	v_add3_u32 v230, s62, v158, v134
	s_waitcnt vmcnt(3)
	ds_write_b128 v224, v[64:67]
	s_waitcnt vmcnt(2)
	ds_write_b128 v230, v[68:71]
	s_waitcnt vmcnt(1)
	ds_read_b128 a[156:159], v234 offset:41568
	s_waitcnt lgkmcnt(5)
	v_mfma_f32_32x32x16_bf16 a[48:63], a[144:147], a[160:163], a[48:63]
	ds_write_b128 v224, v[72:75] offset:9216
	s_waitcnt vmcnt(0)
	ds_write_b128 v230, v[76:79] offset:9216
	v_lshl_add_u64 v[98:99], v[90:91], 0, v[156:157]
	global_load_dwordx4 v[140:143], v[98:99], off
	v_lshl_add_u64 v[98:99], v[92:93], 0, v[156:157]
	global_load_dwordx4 v[144:147], v[98:99], off
	v_lshl_add_u64 v[98:99], v[94:95], 0, v[156:157]
	v_mfma_f32_32x32x16_bf16 a[64:79], a[144:147], a[176:179], a[64:79]
	global_load_dwordx4 v[220:223], v[98:99], off
	v_lshl_add_u64 v[98:99], v[96:97], 0, v[156:157]
	global_load_dwordx4 v[226:229], v[98:99], off
	v_lshl_add_u64 v[90:91], v[90:91], 0, s[56:57]
	v_lshl_add_u64 v[92:93], v[92:93], 0, s[56:57]
	v_lshl_add_u64 v[94:95], v[94:95], 0, s[56:57]
	v_lshl_add_u64 v[96:97], v[96:97], 0, s[56:57]
	ds_read_b128 a[144:147], v234 offset:46080
	s_waitcnt lgkmcnt(7)
	v_mfma_f32_32x32x16_bf16 a[48:63], a[148:151], a[164:167], a[48:63]
	v_exp_f32_e32 v172, v172
	v_exp_f32_e32 v173, v173
	v_exp_f32_e32 v174, v174
	v_exp_f32_e32 v175, v175
	v_mfma_f32_32x32x16_bf16 a[64:79], a[148:151], a[180:183], a[64:79]
	v_exp_f32_e32 v176, v176
	v_exp_f32_e32 v177, v177
	v_exp_f32_e32 v178, v178
	v_exp_f32_e32 v179, v179
	ds_read_b128 a[148:151], v234 offset:46112
	s_waitcnt lgkmcnt(7)
	v_mfma_f32_32x32x16_bf16 a[48:63], a[152:155], a[168:171], a[48:63]
	v_exp_f32_e32 v180, v180
	v_exp_f32_e32 v181, v181
	v_exp_f32_e32 v182, v182
	v_mfma_f32_32x32x16_bf16 a[64:79], a[152:155], a[184:187], a[64:79]
	v_exp_f32_e32 v183, v183
	v_exp_f32_e32 v184, v184
	v_exp_f32_e32 v185, v185
	v_exp_f32_e32 v186, v186
	ds_read_b128 a[152:155], v234 offset:46144
	s_waitcnt lgkmcnt(5)
	v_mfma_f32_32x32x16_bf16 a[48:63], a[156:159], a[172:175], a[48:63]
	v_exp_f32_e32 v187, v187
	v_pk_add_f32 v[148:149], v[172:173], v[174:175]
	v_pk_add_f32 v[148:149], v[148:149], v[176:177]
	v_pk_add_f32 v[148:149], v[148:149], v[178:179]
	v_mfma_f32_32x32x16_bf16 a[64:79], a[156:159], a[188:191], a[64:79]
	v_pk_add_f32 v[148:149], v[148:149], v[180:181]
	v_pk_add_f32 v[148:149], v[148:149], v[182:183]
	v_pk_add_f32 v[148:149], v[148:149], v[184:185]
	v_pk_add_f32 v[148:149], v[148:149], v[186:187]
	v_cvt_pk_bf16_f32 v116, v172, v173
	ds_read_b128 a[156:159], v234 offset:46176
	s_waitcnt lgkmcnt(3)
	v_mfma_f32_32x32x16_bf16 a[80:95], a[144:147], a[160:163], a[80:95]
	v_cvt_pk_bf16_f32 v117, v174, v175
	v_cvt_pk_bf16_f32 v118, v176, v177
	v_cvt_pk_bf16_f32 v119, v178, v179
	v_cvt_pk_bf16_f32 v120, v180, v181
	v_cvt_pk_bf16_f32 v121, v182, v183
	v_cvt_pk_bf16_f32 v122, v184, v185
	v_cvt_pk_bf16_f32 v123, v186, v187
	v_mfma_f32_32x32x16_bf16 a[96:111], a[144:147], a[176:179], a[96:111]
	v_exp_f32_e32 v204, v204
	v_exp_f32_e32 v205, v205
	v_exp_f32_e32 v206, v206
	v_exp_f32_e32 v207, v207
	ds_read_b128 a[144:147], v234 offset:50688
	s_waitcnt lgkmcnt(3)
	v_mfma_f32_32x32x16_bf16 a[80:95], a[148:151], a[164:167], a[80:95]
	v_exp_f32_e32 v208, v208
	v_exp_f32_e32 v209, v209
	v_exp_f32_e32 v210, v210
	v_exp_f32_e32 v211, v211
	v_mfma_f32_32x32x16_bf16 a[96:111], a[148:151], a[180:183], a[96:111]
	v_exp_f32_e32 v212, v212
	v_exp_f32_e32 v213, v213
	v_exp_f32_e32 v214, v214
	ds_read_b128 a[148:151], v234 offset:50720
	s_waitcnt lgkmcnt(3)
	v_mfma_f32_32x32x16_bf16 a[80:95], a[152:155], a[168:171], a[80:95]
	v_exp_f32_e32 v215, v215
	v_exp_f32_e32 v216, v216
	v_exp_f32_e32 v217, v217
	v_exp_f32_e32 v218, v218
	v_mfma_f32_32x32x16_bf16 a[96:111], a[152:155], a[184:187], a[96:111]
	v_exp_f32_e32 v219, v219
	v_pk_add_f32 v[136:137], v[136:137], v[204:205]
	v_pk_add_f32 v[136:137], v[136:137], v[206:207]
	v_pk_add_f32 v[136:137], v[136:137], v[208:209]
	ds_read_b128 a[152:155], v234 offset:50752
	s_waitcnt lgkmcnt(3)
	v_mfma_f32_32x32x16_bf16 a[80:95], a[156:159], a[172:175], a[80:95]
	v_pk_add_f32 v[136:137], v[136:137], v[210:211]
	v_pk_add_f32 v[136:137], v[136:137], v[212:213]
	v_pk_add_f32 v[136:137], v[136:137], v[214:215]
	v_pk_add_f32 v[136:137], v[136:137], v[216:217]
	v_mfma_f32_32x32x16_bf16 a[96:111], a[156:159], a[188:191], a[96:111]
	v_pk_add_f32 v[136:137], v[136:137], v[218:219]
	v_cvt_pk_bf16_f32 v56, v204, v205
	v_cvt_pk_bf16_f32 v57, v206, v207
	v_cvt_pk_bf16_f32 v58, v208, v209
	v_cvt_pk_bf16_f32 v59, v210, v211
	v_cvt_pk_bf16_f32 v60, v212, v213
	v_cvt_pk_bf16_f32 v61, v214, v215
	ds_read_b128 a[156:159], v234 offset:50784
	s_waitcnt lgkmcnt(3)
	v_mfma_f32_32x32x16_bf16 a[32:47], a[144:147], a[160:163], a[32:47]
	v_cvt_pk_bf16_f32 v62, v216, v217
	v_cvt_pk_bf16_f32 v63, v218, v219
	v_add_f32_e32 v235, v136, v137
	v_add_f32_e32 v81, v81, v235
	v_exp_f32_e32 v100, v100
	v_exp_f32_e32 v101, v101
	v_mfma_f32_32x32x16_bf16 a[16:31], a[144:147], a[176:179], a[16:31]
	v_exp_f32_e32 v102, v102
	v_exp_f32_e32 v103, v103
	v_exp_f32_e32 v104, v104
	s_waitcnt lgkmcnt(2)
	v_mfma_f32_32x32x16_bf16 a[32:47], a[148:151], a[164:167], a[32:47]
	v_exp_f32_e32 v105, v105
	v_exp_f32_e32 v106, v106
	v_exp_f32_e32 v107, v107
	v_exp_f32_e32 v108, v108
	v_mfma_f32_32x32x16_bf16 a[16:31], a[148:151], a[180:183], a[16:31]
	v_exp_f32_e32 v109, v109
	v_exp_f32_e32 v110, v110
	v_exp_f32_e32 v111, v111
	v_exp_f32_e32 v112, v112
	s_waitcnt lgkmcnt(1)
	v_mfma_f32_32x32x16_bf16 a[32:47], a[152:155], a[168:171], a[32:47]
	v_exp_f32_e32 v113, v113
	v_exp_f32_e32 v114, v114
	v_exp_f32_e32 v115, v115
	v_pk_add_f32 v[148:149], v[148:149], v[100:101]
	v_mfma_f32_32x32x16_bf16 a[16:31], a[152:155], a[184:187], a[16:31]
	v_pk_add_f32 v[148:149], v[148:149], v[102:103]
	v_pk_add_f32 v[148:149], v[148:149], v[104:105]
	v_pk_add_f32 v[148:149], v[148:149], v[106:107]
	v_pk_add_f32 v[148:149], v[148:149], v[108:109]
	s_waitcnt lgkmcnt(0)
	v_mfma_f32_32x32x16_bf16 a[32:47], a[156:159], a[172:175], a[32:47]
	v_pk_add_f32 v[148:149], v[148:149], v[110:111]
	v_pk_add_f32 v[148:149], v[148:149], v[112:113]
	v_pk_add_f32 v[148:149], v[148:149], v[114:115]
	v_cvt_pk_bf16_f32 v124, v100, v101
	v_cvt_pk_bf16_f32 v125, v102, v103
	v_mfma_f32_32x32x16_bf16 a[16:31], a[156:159], a[188:191], a[16:31]
	v_cvt_pk_bf16_f32 v126, v104, v105
	v_cvt_pk_bf16_f32 v127, v106, v107
	v_cvt_pk_bf16_f32 v130, v108, v109
	v_cvt_pk_bf16_f32 v131, v110, v111
	v_cvt_pk_bf16_f32 v132, v112, v113
	v_cvt_pk_bf16_f32 v133, v114, v115
	v_add_f32_e32 v235, v148, v149
	v_add_f32_e32 v80, v80, v235
	s_add_i32 s60, s60, 1
	s_cmp_eq_u32 s8, s60
	s_cbranch_scc0 .LBB0_1087
	s_waitcnt vmcnt(0) lgkmcnt(0)
	s_barrier
	v_add3_u32 v224, s62, v153, v134
	v_add3_u32 v230, s62, v158, v134
	v_add3_u32 v231, s62, v159, v134
	v_add3_u32 v232, s62, v160, v134
	ds_write_b128 v224, v[140:143] offset:36864
	ds_write_b128 v230, v[144:147] offset:36864
	ds_write_b128 v231, v[220:223] offset:36864
	ds_write_b128 v232, v[226:229] offset:36864
	v_add_u32_e32 v234, s61, v152
	ds_read_b128 a[144:147], v234 offset:36864
	ds_read_b128 a[148:151], v234 offset:36896
	ds_read_b128 a[152:155], v234 offset:36928
	ds_read_b128 a[156:159], v234 offset:36960
	s_waitcnt lgkmcnt(3)
	v_mfma_f32_32x32x16_bf16 a[128:143], a[144:147], v[48:51], a[128:143]
	v_mfma_f32_32x32x16_bf16 a[112:127], a[144:147], v[116:119], a[112:127]
	ds_read_b128 a[144:147], v234 offset:41472
	s_waitcnt lgkmcnt(3)
	v_mfma_f32_32x32x16_bf16 a[128:143], a[148:151], v[52:55], a[128:143]
	v_mfma_f32_32x32x16_bf16 a[112:127], a[148:151], v[120:123], a[112:127]
	ds_read_b128 a[148:151], v234 offset:41504
	s_waitcnt lgkmcnt(3)
	v_mfma_f32_32x32x16_bf16 a[128:143], a[152:155], v[56:59], a[128:143]
	v_mfma_f32_32x32x16_bf16 a[112:127], a[152:155], v[124:127], a[112:127]
	ds_read_b128 a[152:155], v234 offset:41536
	s_waitcnt lgkmcnt(3)
	v_mfma_f32_32x32x16_bf16 a[128:143], a[156:159], v[60:63], a[128:143]
	v_mfma_f32_32x32x16_bf16 a[112:127], a[156:159], v[130:133], a[112:127]
	ds_read_b128 a[156:159], v234 offset:41568
	s_waitcnt lgkmcnt(3)
	v_mfma_f32_32x32x16_bf16 a[48:63], a[144:147], v[48:51], a[48:63]
	v_mfma_f32_32x32x16_bf16 a[64:79], a[144:147], v[116:119], a[64:79]
	ds_read_b128 a[144:147], v234 offset:46080
	s_waitcnt lgkmcnt(3)
	v_mfma_f32_32x32x16_bf16 a[48:63], a[148:151], v[52:55], a[48:63]
	v_mfma_f32_32x32x16_bf16 a[64:79], a[148:151], v[120:123], a[64:79]
	ds_read_b128 a[148:151], v234 offset:46112
	s_waitcnt lgkmcnt(3)
	v_mfma_f32_32x32x16_bf16 a[48:63], a[152:155], v[56:59], a[48:63]
	v_mfma_f32_32x32x16_bf16 a[64:79], a[152:155], v[124:127], a[64:79]
	ds_read_b128 a[152:155], v234 offset:46144
	s_waitcnt lgkmcnt(3)
	v_mfma_f32_32x32x16_bf16 a[48:63], a[156:159], v[60:63], a[48:63]
	v_mfma_f32_32x32x16_bf16 a[64:79], a[156:159], v[130:133], a[64:79]
	ds_read_b128 a[156:159], v234 offset:46176
	s_waitcnt lgkmcnt(3)
	v_mfma_f32_32x32x16_bf16 a[80:95], a[144:147], v[48:51], a[80:95]
	v_mfma_f32_32x32x16_bf16 a[96:111], a[144:147], v[116:119], a[96:111]
	ds_read_b128 a[144:147], v234 offset:50688
	s_waitcnt lgkmcnt(3)
	v_mfma_f32_32x32x16_bf16 a[80:95], a[148:151], v[52:55], a[80:95]
	v_mfma_f32_32x32x16_bf16 a[96:111], a[148:151], v[120:123], a[96:111]
	ds_read_b128 a[148:151], v234 offset:50720
	s_waitcnt lgkmcnt(3)
	v_mfma_f32_32x32x16_bf16 a[80:95], a[152:155], v[56:59], a[80:95]
	v_mfma_f32_32x32x16_bf16 a[96:111], a[152:155], v[124:127], a[96:111]
	ds_read_b128 a[152:155], v234 offset:50752
	s_waitcnt lgkmcnt(3)
	v_mfma_f32_32x32x16_bf16 a[80:95], a[156:159], v[60:63], a[80:95]
	v_mfma_f32_32x32x16_bf16 a[96:111], a[156:159], v[130:133], a[96:111]
	ds_read_b128 a[156:159], v234 offset:50784
	s_waitcnt lgkmcnt(3)
	v_mfma_f32_32x32x16_bf16 a[32:47], a[144:147], v[48:51], a[32:47]
	v_mfma_f32_32x32x16_bf16 a[16:31], a[144:147], v[116:119], a[16:31]
	s_waitcnt lgkmcnt(2)
	v_mfma_f32_32x32x16_bf16 a[32:47], a[148:151], v[52:55], a[32:47]
	v_mfma_f32_32x32x16_bf16 a[16:31], a[148:151], v[120:123], a[16:31]
	s_waitcnt lgkmcnt(1)
	v_mfma_f32_32x32x16_bf16 a[32:47], a[152:155], v[56:59], a[32:47]
	v_mfma_f32_32x32x16_bf16 a[16:31], a[152:155], v[124:127], a[16:31]
	s_waitcnt lgkmcnt(0)
	v_mfma_f32_32x32x16_bf16 a[32:47], a[156:159], v[60:63], a[32:47]
	v_mfma_f32_32x32x16_bf16 a[16:31], a[156:159], v[130:133], a[16:31]
	s_bitcmp1_b32 s8, 0
	s_cselect_b32 s8, 0x4800, 0
	v_add_u32_e32 v48, s8, v128
	s_waitcnt lgkmcnt(0)
	s_barrier
	ds_read_b128 v[32:35], v48
	ds_read_b128 v[36:39], v48 offset:32
	s_waitcnt lgkmcnt(1)
	v_mfma_f32_32x32x16_bf16 a[186:201], v[32:35], v[28:31], a[0:15]
	v_add_u32_e32 v83, s8, v152
	v_mfma_f32_32x32x16_bf16 a[144:159], v[32:35], v[12:15], a[0:15]
	s_waitcnt lgkmcnt(0)
	v_mfma_f32_32x32x16_bf16 a[186:201], v[36:39], v[24:27], a[186:201]
	v_mfma_f32_32x32x16_bf16 a[144:159], v[36:39], v[8:11], a[144:159]
	ds_read_b128 v[32:35], v48 offset:64
	ds_read_b128 v[36:39], v48 offset:96
	s_waitcnt lgkmcnt(1)
	v_mfma_f32_32x32x16_bf16 a[186:201], v[32:35], v[20:23], a[186:201]
	s_waitcnt lgkmcnt(0)
	v_mfma_f32_32x32x16_bf16 a[186:201], v[36:39], v[16:19], a[186:201]
	v_mfma_f32_32x32x16_bf16 a[144:159], v[32:35], v[4:7], a[144:159]
	ds_read_b128 v[32:35], v48 offset:4608
	ds_read_b128 v[40:43], v48 offset:4640
	ds_read_b128 v[44:47], v48 offset:4672
	ds_read_b128 v[48:51], v48 offset:4704
	s_nop 6
	v_accvgpr_read_b32 v52, a186
	v_accvgpr_read_b32 v53, a187
	v_accvgpr_read_b32 v54, a188
	v_exp_f32_e32 v52, v52
	v_exp_f32_e32 v53, v53
	s_waitcnt lgkmcnt(3)
	v_mfma_f32_32x32x16_bf16 a[172:187], v[32:35], v[28:31], a[0:15]
	v_accvgpr_read_b32 v28, a189
	v_exp_f32_e32 v55, v28
	v_accvgpr_read_b32 v28, a190
	v_exp_f32_e32 v56, v28
	v_accvgpr_read_b32 v28, a191
	v_exp_f32_e32 v54, v54
	v_exp_f32_e32 v57, v28
	s_waitcnt lgkmcnt(2)
	v_mfma_f32_32x32x16_bf16 a[172:187], v[40:43], v[24:27], a[172:187]
	v_accvgpr_read_b32 v24, a192
	v_exp_f32_e32 v58, v24
	v_accvgpr_read_b32 v24, a193
	v_exp_f32_e32 v59, v24
	v_accvgpr_read_b32 v24, a194
	v_exp_f32_e32 v60, v24
	v_accvgpr_read_b32 v24, a195
	s_waitcnt lgkmcnt(1)
	v_mfma_f32_32x32x16_bf16 a[172:187], v[44:47], v[20:23], a[172:187]
	v_accvgpr_read_b32 v20, a196
	v_exp_f32_e32 v62, v20
	v_accvgpr_read_b32 v20, a197
	v_exp_f32_e32 v63, v20
	v_accvgpr_read_b32 v20, a198
	v_exp_f32_e32 v64, v20
	v_exp_f32_e32 v61, v24
	s_waitcnt lgkmcnt(0)
	v_mfma_f32_32x32x16_bf16 a[172:187], v[48:51], v[16:19], a[172:187]
	v_accvgpr_read_b32 v16, a199
	v_exp_f32_e32 v65, v16
	v_accvgpr_read_b32 v16, a200
	v_exp_f32_e32 v66, v16
	v_accvgpr_read_b32 v16, a201
	v_exp_f32_e32 v67, v16
	ds_read_b128 v[28:31], v83 offset:36928
	v_mfma_f32_32x32x16_bf16 a[144:159], v[36:39], v[0:3], a[144:159]
	s_nop 3
	v_accvgpr_read_b32 v16, a172
	v_exp_f32_e32 v36, v16
	v_accvgpr_read_b32 v16, a173
	v_exp_f32_e32 v37, v16
	v_accvgpr_read_b32 v16, a174
	v_exp_f32_e32 v38, v16
	v_accvgpr_read_b32 v16, a175
	v_mfma_f32_32x32x16_bf16 a[160:175], v[32:35], v[12:15], a[0:15]
	v_exp_f32_e32 v39, v16
	v_accvgpr_read_b32 v16, a144
	v_accvgpr_read_b32 v12, a176
	v_exp_f32_e32 v68, v12
	v_accvgpr_read_b32 v12, a177
	v_accvgpr_read_b32 v20, a157
	v_exp_f32_e32 v69, v12
	v_mfma_f32_32x32x16_bf16 a[160:175], v[40:43], v[8:11], a[160:175]
	v_accvgpr_read_b32 v12, a178
	v_exp_f32_e32 v84, v20
	v_accvgpr_read_b32 v20, a158
	v_exp_f32_e32 v70, v12
	v_accvgpr_read_b32 v12, a179
	v_exp_f32_e32 v85, v20
	v_accvgpr_read_b32 v20, a159
	v_mfma_f32_32x32x16_bf16 a[160:175], v[44:47], v[4:7], a[160:175]
	v_exp_f32_e32 v40, v12
	v_cvt_pk_bf16_f32 v12, v52, v53
	v_cvt_pk_bf16_f32 v13, v54, v55
	v_cvt_pk_bf16_f32 v14, v56, v57
	v_cvt_pk_bf16_f32 v15, v58, v59
	v_exp_f32_e32 v86, v20
	ds_read_b128 v[20:23], v83 offset:36896
	v_mfma_f32_32x32x16_bf16 a[160:175], v[48:51], v[0:3], a[160:175]
	v_exp_f32_e32 v49, v16
	v_accvgpr_read_b32 v16, a145
	v_exp_f32_e32 v50, v16
	v_accvgpr_read_b32 v16, a146
	v_exp_f32_e32 v51, v16
	v_accvgpr_read_b32 v16, a147
	v_exp_f32_e32 v71, v16
	v_accvgpr_read_b32 v16, a148
	v_exp_f32_e32 v72, v16
	v_accvgpr_read_b32 v16, a149
	v_exp_f32_e32 v73, v16
	v_accvgpr_read_b32 v16, a150
	v_exp_f32_e32 v74, v16
	v_accvgpr_read_b32 v16, a151
	v_exp_f32_e32 v75, v16
	v_accvgpr_read_b32 v16, a152
	v_exp_f32_e32 v76, v16
	v_accvgpr_read_b32 v16, a153
	v_exp_f32_e32 v77, v16
	v_accvgpr_read_b32 v16, a154
	v_exp_f32_e32 v78, v16
	v_accvgpr_read_b32 v16, a155
	v_exp_f32_e32 v79, v16
	v_accvgpr_read_b32 v16, a156
	v_exp_f32_e32 v82, v16
	ds_read_b128 v[16:19], v83 offset:36864
	v_accvgpr_read_b32 v24, a160
	v_exp_f32_e32 v87, v24
	v_accvgpr_read_b32 v24, a161
	v_exp_f32_e32 v88, v24
	v_cvt_pk_bf16_f32 v24, v49, v50
	v_cvt_pk_bf16_f32 v25, v51, v71
	v_cvt_pk_bf16_f32 v26, v72, v73
	v_cvt_pk_bf16_f32 v27, v74, v75
	s_waitcnt lgkmcnt(0)
	v_mfma_f32_32x32x16_bf16 a[144:159], v[16:19], v[12:15], a[128:143]
	v_accvgpr_read_b32 v8, a180
	v_exp_f32_e32 v41, v8
	v_accvgpr_read_b32 v8, a181
	v_exp_f32_e32 v42, v8
	v_accvgpr_read_b32 v8, a182
	v_exp_f32_e32 v43, v8
	v_cvt_pk_bf16_f32 v8, v60, v61
	v_mfma_f32_32x32x16_bf16 a[128:143], v[16:19], v[24:27], a[112:127]
	v_accvgpr_read_b32 v16, a162
	v_exp_f32_e32 v89, v16
	v_accvgpr_read_b32 v16, a163
	v_exp_f32_e32 v90, v16
	v_accvgpr_read_b32 v16, a164
	v_exp_f32_e32 v91, v16
	v_accvgpr_read_b32 v16, a165
	v_cvt_pk_bf16_f32 v9, v62, v63
	v_cvt_pk_bf16_f32 v10, v64, v65
	v_cvt_pk_bf16_f32 v11, v66, v67
	v_exp_f32_e32 v92, v16
	v_cvt_pk_bf16_f32 v16, v76, v77
	v_cvt_pk_bf16_f32 v17, v78, v79
	v_cvt_pk_bf16_f32 v18, v82, v84
	v_cvt_pk_bf16_f32 v19, v85, v86
	v_mfma_f32_32x32x16_bf16 a[144:159], v[20:23], v[8:11], a[144:159]
	v_accvgpr_read_b32 v32, a166
	v_accvgpr_read_b32 v4, a183
	v_exp_f32_e32 v93, v32
	v_exp_f32_e32 v44, v4
	v_accvgpr_read_b32 v4, a184
	v_exp_f32_e32 v45, v4
	v_accvgpr_read_b32 v4, a185
	v_mfma_f32_32x32x16_bf16 a[128:143], v[20:23], v[16:19], a[128:143]
	v_accvgpr_read_b32 v20, a167
	v_exp_f32_e32 v94, v20
	v_accvgpr_read_b32 v32, a169
	v_exp_f32_e32 v46, v4
	v_accvgpr_read_b32 v4, a186
	v_exp_f32_e32 v96, v32
	v_accvgpr_read_b32 v32, a170
	v_exp_f32_e32 v47, v4
	v_cvt_pk_bf16_f32 v4, v36, v37
	v_cvt_pk_bf16_f32 v5, v38, v39
	v_cvt_pk_bf16_f32 v6, v68, v69
	v_cvt_pk_bf16_f32 v7, v70, v40
	v_accvgpr_read_b32 v20, a168
	v_exp_f32_e32 v97, v32
	v_cvt_pk_bf16_f32 v32, v87, v88
	v_cvt_pk_bf16_f32 v33, v89, v90
	v_cvt_pk_bf16_f32 v34, v91, v92
	v_cvt_pk_bf16_f32 v35, v93, v94
	v_exp_f32_e32 v95, v20
	ds_read_b128 v[20:23], v83 offset:36960
	v_mfma_f32_32x32x16_bf16 a[144:159], v[28:31], v[4:7], a[144:159]
	v_accvgpr_read_b32 v0, a187
	v_exp_f32_e32 v48, v0
	v_cvt_pk_bf16_f32 v0, v41, v42
	v_cvt_pk_bf16_f32 v1, v43, v44
	v_cvt_pk_bf16_f32 v2, v45, v46
	v_cvt_pk_bf16_f32 v3, v47, v48
	v_cvt_pk_bf16_f32 v130, v95, v96
	v_mfma_f32_32x32x16_bf16 a[128:143], v[28:31], v[32:35], a[128:143]
	v_accvgpr_read_b32 v28, a171
	v_exp_f32_e32 v98, v28
	v_accvgpr_read_b32 v28, a172
	v_exp_f32_e32 v99, v28
	v_accvgpr_read_b32 v28, a173
	v_exp_f32_e32 v100, v28
	v_accvgpr_read_b32 v28, a174
	v_exp_f32_e32 v101, v28
	v_accvgpr_read_b32 v28, a175
	v_exp_f32_e32 v102, v28
	v_cvt_pk_bf16_f32 v131, v97, v98
	v_cvt_pk_bf16_f32 v132, v99, v100
	s_waitcnt lgkmcnt(0)
	v_mfma_f32_32x32x16_bf16 a[144:159], v[20:23], v[0:3], a[144:159]
	v_cvt_pk_bf16_f32 v133, v101, v102
	s_nop 1
	v_mfma_f32_32x32x16_bf16 a[128:143], v[20:23], v[130:133], a[128:143]
	ds_read_b128 v[20:23], v83 offset:41472
	ds_read_b128 v[28:31], v83 offset:41504
	s_nop 5
	v_accvgpr_read_b32 v112, a144
	v_accvgpr_read_b32 v113, a145
	v_accvgpr_read_b32 v114, a146
	v_accvgpr_read_b32 v115, a147
	s_waitcnt lgkmcnt(1)
	v_mfma_f32_32x32x16_bf16 a[112:127], v[20:23], v[12:15], a[48:63]
	v_accvgpr_read_b32 v116, a148
	v_accvgpr_read_b32 v117, a149
	v_accvgpr_read_b32 v118, a150
	v_accvgpr_read_b32 v119, a151
	v_accvgpr_read_b32 v120, a152
	v_accvgpr_read_b32 v121, a153
	v_accvgpr_read_b32 v122, a154
	v_mfma_f32_32x32x16_bf16 a[48:63], v[20:23], v[24:27], a[64:79]
	v_accvgpr_read_b32 v123, a155
	v_accvgpr_read_b32 v124, a156
	v_accvgpr_read_b32 v125, a157
	v_accvgpr_read_b32 v126, a158
	v_accvgpr_read_b32 v127, a159
	s_waitcnt lgkmcnt(0)
	v_mfma_f32_32x32x16_bf16 a[112:127], v[28:31], v[8:11], a[112:127]
	v_mfma_f32_32x32x16_bf16 a[48:63], v[28:31], v[16:19], a[48:63]
	ds_read_b128 v[20:23], v83 offset:41536
	ds_read_b128 v[28:31], v83 offset:41568
	s_waitcnt lgkmcnt(1)
	v_mfma_f32_32x32x16_bf16 a[112:127], v[20:23], v[4:7], a[112:127]
	v_mfma_f32_32x32x16_bf16 a[48:63], v[20:23], v[32:35], a[48:63]
	s_waitcnt lgkmcnt(0)
	v_mfma_f32_32x32x16_bf16 a[112:127], v[28:31], v[0:3], a[112:127]
	v_mfma_f32_32x32x16_bf16 a[48:63], v[28:31], v[130:133], a[48:63]
	ds_read_b128 v[20:23], v83 offset:46080
	ds_read_b128 v[28:31], v83 offset:46112
	s_waitcnt lgkmcnt(1)
	v_mfma_f32_32x32x16_bf16 a[64:79], v[20:23], v[12:15], a[80:95]
	v_mfma_f32_32x32x16_bf16 a[80:95], v[20:23], v[24:27], a[96:111]
	ds_read_b128 v[20:23], v83 offset:46144
	s_waitcnt lgkmcnt(1)
	v_mfma_f32_32x32x16_bf16 a[64:79], v[28:31], v[8:11], a[64:79]
	v_mfma_f32_32x32x16_bf16 a[80:95], v[28:31], v[16:19], a[80:95]
	v_add_f32_e32 v28, 0, v52
	v_add_f32_e32 v28, v53, v28
	v_add_f32_e32 v28, v54, v28
	v_add_f32_e32 v28, v55, v28
	v_add_f32_e32 v52, v56, v28
	v_add_f32_e32 v52, v57, v52
	v_add_f32_e32 v52, v58, v52
	v_add_f32_e32 v52, v59, v52
	v_add_f32_e32 v52, v60, v52
	v_add_f32_e32 v52, v61, v52
	v_add_f32_e32 v52, v62, v52
	v_add_f32_e32 v52, v63, v52
	ds_read_b128 v[28:31], v83 offset:46176
	s_waitcnt lgkmcnt(1)
	v_mfma_f32_32x32x16_bf16 a[64:79], v[20:23], v[4:7], a[64:79]
	v_mfma_f32_32x32x16_bf16 a[80:95], v[20:23], v[32:35], a[80:95]
	v_add_f32_e32 v20, v64, v52
	v_add_f32_e32 v20, v65, v20
	v_add_f32_e32 v20, v66, v20
	v_add_f32_e32 v20, v67, v20
	v_add_f32_e32 v20, v36, v20
	v_add_f32_e32 v20, v37, v20
	v_add_f32_e32 v20, v38, v20
	v_add_f32_e32 v20, v39, v20
	v_add_f32_e32 v20, v68, v20
	v_add_f32_e32 v20, v69, v20
	v_add_f32_e32 v20, v70, v20
	v_add_f32_e32 v20, v40, v20
	v_add_f32_e32 v36, v41, v20
	ds_read_b128 v[20:23], v83 offset:50688
	s_waitcnt lgkmcnt(1)
	v_mfma_f32_32x32x16_bf16 a[64:79], v[28:31], v[0:3], a[64:79]
	v_mfma_f32_32x32x16_bf16 a[80:95], v[28:31], v[130:133], a[80:95]
	v_add_f32_e32 v28, v42, v36
	v_add_f32_e32 v28, v43, v28
	v_add_f32_e32 v28, v44, v28
	v_add_f32_e32 v28, v45, v28
	v_add_f32_e32 v28, v46, v28
	v_add_f32_e32 v36, v47, v28
	ds_read_b128 v[28:31], v83 offset:50720
	s_waitcnt lgkmcnt(1)
	v_mfma_f32_32x32x16_bf16 a[96:111], v[20:23], v[12:15], a[32:47]
	v_add_f32_e32 v12, v48, v36
	v_add_f32_e32 v136, v81, v12
	v_add_f32_e32 v12, 0, v49
	v_add_f32_e32 v12, v50, v12
	v_add_f32_e32 v12, v51, v12
	v_add_f32_e32 v12, v71, v12
	v_add_f32_e32 v12, v72, v12
	v_add_f32_e32 v12, v73, v12
	v_add_f32_e32 v12, v74, v12
	v_add_f32_e32 v12, v75, v12
	v_add_f32_e32 v12, v76, v12
	v_add_f32_e32 v12, v77, v12
	v_add_f32_e32 v12, v78, v12
	v_add_f32_e32 v12, v79, v12
	s_waitcnt lgkmcnt(0)
	v_mfma_f32_32x32x16_bf16 a[96:111], v[28:31], v[8:11], a[96:111]
	v_add_f32_e32 v8, v82, v12
	v_add_f32_e32 v8, v84, v8
	v_add_f32_e32 v8, v85, v8
	v_add_f32_e32 v8, v86, v8
	v_add_f32_e32 v8, v87, v8
	v_add_f32_e32 v12, v88, v8
	ds_read_b128 v[8:11], v83 offset:50752
	v_mfma_f32_32x32x16_bf16 a[32:47], v[20:23], v[24:27], a[16:31]
	v_add_f32_e32 v12, v89, v12
	v_add_f32_e32 v12, v90, v12
	v_add_f32_e32 v12, v91, v12
	v_add_f32_e32 v12, v92, v12
	v_add_f32_e32 v12, v93, v12
	v_accvgpr_read_b32 v48, a128
	v_accvgpr_read_b32 v49, a129
	v_mfma_f32_32x32x16_bf16 a[32:47], v[28:31], v[16:19], a[32:47]
	v_add_f32_e32 v16, v94, v12
	ds_read_b128 v[12:15], v83 offset:50784
	v_accvgpr_read_b32 v50, a130
	v_accvgpr_read_b32 v51, a131
	v_accvgpr_read_b32 v52, a132
	v_accvgpr_read_b32 v53, a133
	v_accvgpr_read_b32 v54, a134
	s_waitcnt lgkmcnt(1)
	v_mfma_f32_32x32x16_bf16 a[96:111], v[8:11], v[4:7], a[96:111]
	v_add_f32_e32 v4, v95, v16
	v_add_f32_e32 v4, v96, v4
	v_add_f32_e32 v4, v97, v4
	v_add_f32_e32 v4, v98, v4
	v_add_f32_e32 v4, v99, v4
	v_add_f32_e32 v4, v100, v4
	v_add_f32_e32 v4, v101, v4
	v_add_f32_e32 v4, v102, v4
	v_add_f32_e32 v137, v80, v4
	ds_bpermute_b32 v4, v161, v136
	v_mfma_f32_32x32x16_bf16 a[32:47], v[8:11], v[32:35], a[32:47]
	v_accvgpr_read_b32 v96, a112
	v_accvgpr_read_b32 v32, a48
	v_accvgpr_read_b32 v95, a79
	s_waitcnt lgkmcnt(0)
	v_add_f32_e32 v136, v136, v4
	v_div_scale_f32 v140, s[60:61], v136, v136, 1.0
	v_rcp_f32_e32 v141, v140
	v_mfma_f32_32x32x16_bf16 a[32:47], v[12:15], v[130:133], a[32:47]
	ds_bpermute_b32 v131, v161, v137
	v_accvgpr_read_b32 v16, a80
	v_fma_f32 v130, -v140, v141, 1.0
	v_fmac_f32_e32 v141, v130, v141
	v_div_scale_f32 v130, vcc, 1.0, v136, 1.0
	v_mul_f32_e32 v132, v130, v141
	v_fma_f32 v133, -v140, v132, v130
	s_waitcnt lgkmcnt(0)
	v_add_f32_e32 v131, v137, v131
	v_fmac_f32_e32 v132, v133, v141
	v_div_scale_f32 v133, s[60:61], v131, v131, 1.0
	v_rcp_f32_e32 v137, v133
	v_mfma_f32_32x32x16_bf16 a[96:111], v[12:15], v[0:3], a[96:111]
	v_fma_f32 v130, -v140, v132, v130
	v_div_fmas_f32 v130, v130, v141, v132
	v_div_fixup_f32 v224, v130, v136, 1.0
	v_fma_f32 v130, -v133, v137, 1.0
	v_fmac_f32_e32 v137, v130, v137
	v_div_scale_f32 v130, vcc, 1.0, v131, 1.0
	v_mul_f32_e32 v132, v130, v137
	v_fma_f32 v136, -v133, v132, v130
	v_fmac_f32_e32 v132, v136, v137
	v_fma_f32 v130, -v133, v132, v130
	v_accvgpr_read_b32 v0, a32
	s_nop 0
	v_accvgpr_read_b32 v64, a96
	v_div_fmas_f32 v130, v130, v137, v132
	v_accvgpr_read_b32 v55, a135
	v_accvgpr_read_b32 v56, a136
	v_accvgpr_read_b32 v57, a137
	v_accvgpr_read_b32 v58, a138
	v_accvgpr_read_b32 v59, a139
	v_accvgpr_read_b32 v60, a140
	v_accvgpr_read_b32 v61, a141
	v_accvgpr_read_b32 v62, a142
	v_accvgpr_read_b32 v63, a143
	v_accvgpr_read_b32 v97, a113
	v_accvgpr_read_b32 v98, a114
	v_accvgpr_read_b32 v99, a115
	v_accvgpr_read_b32 v100, a116
	v_accvgpr_read_b32 v101, a117
	v_accvgpr_read_b32 v102, a118
	v_accvgpr_read_b32 v103, a119
	v_accvgpr_read_b32 v104, a120
	v_accvgpr_read_b32 v105, a121
	v_accvgpr_read_b32 v106, a122
	v_accvgpr_read_b32 v107, a123
	v_accvgpr_read_b32 v108, a124
	v_accvgpr_read_b32 v109, a125
	v_accvgpr_read_b32 v110, a126
	v_accvgpr_read_b32 v111, a127
	v_accvgpr_read_b32 v33, a49
	v_accvgpr_read_b32 v34, a50
	v_accvgpr_read_b32 v35, a51
	v_accvgpr_read_b32 v36, a52
	v_accvgpr_read_b32 v37, a53
	v_accvgpr_read_b32 v38, a54
	v_accvgpr_read_b32 v39, a55
	v_accvgpr_read_b32 v40, a56
	v_accvgpr_read_b32 v41, a57
	v_accvgpr_read_b32 v42, a58
	v_accvgpr_read_b32 v43, a59
	v_accvgpr_read_b32 v44, a60
	v_accvgpr_read_b32 v45, a61
	v_accvgpr_read_b32 v46, a62
	v_accvgpr_read_b32 v47, a63
	v_accvgpr_read_b32 v94, a78
	v_accvgpr_read_b32 v93, a77
	v_accvgpr_read_b32 v92, a76
	v_accvgpr_read_b32 v91, a75
	v_accvgpr_read_b32 v90, a74
	v_accvgpr_read_b32 v89, a73
	v_accvgpr_read_b32 v88, a72
	v_accvgpr_read_b32 v87, a71
	v_accvgpr_read_b32 v86, a70
	v_accvgpr_read_b32 v85, a69
	v_accvgpr_read_b32 v84, a68
	v_accvgpr_read_b32 v83, a67
	v_accvgpr_read_b32 v82, a66
	v_accvgpr_read_b32 v81, a65
	v_accvgpr_read_b32 v80, a64
	v_accvgpr_read_b32 v17, a81
	v_accvgpr_read_b32 v18, a82
	v_accvgpr_read_b32 v19, a83
	v_accvgpr_read_b32 v20, a84
	v_accvgpr_read_b32 v21, a85
	v_accvgpr_read_b32 v22, a86
	v_accvgpr_read_b32 v23, a87
	v_accvgpr_read_b32 v24, a88
	v_accvgpr_read_b32 v25, a89
	v_accvgpr_read_b32 v26, a90
	v_accvgpr_read_b32 v27, a91
	v_accvgpr_read_b32 v28, a92
	v_accvgpr_read_b32 v29, a93
	v_accvgpr_read_b32 v30, a94
	v_accvgpr_read_b32 v31, a95
	v_accvgpr_read_b32 v65, a97
	v_accvgpr_read_b32 v66, a98
	v_accvgpr_read_b32 v67, a99
	v_accvgpr_read_b32 v68, a100
	v_accvgpr_read_b32 v69, a101
	v_accvgpr_read_b32 v70, a102
	v_accvgpr_read_b32 v71, a103
	v_accvgpr_read_b32 v72, a104
	v_accvgpr_read_b32 v73, a105
	v_accvgpr_read_b32 v74, a106
	v_accvgpr_read_b32 v75, a107
	v_accvgpr_read_b32 v76, a108
	v_accvgpr_read_b32 v77, a109
	v_accvgpr_read_b32 v78, a110
	v_accvgpr_read_b32 v79, a111
	v_accvgpr_read_b32 v1, a33
	v_accvgpr_read_b32 v2, a34
	v_accvgpr_read_b32 v3, a35
	v_accvgpr_read_b32 v4, a36
	v_accvgpr_read_b32 v5, a37
	v_accvgpr_read_b32 v6, a38
	v_accvgpr_read_b32 v7, a39
	v_accvgpr_read_b32 v8, a40
	v_accvgpr_read_b32 v9, a41
	v_accvgpr_read_b32 v10, a42
	v_accvgpr_read_b32 v11, a43
	v_accvgpr_read_b32 v12, a44
	v_accvgpr_read_b32 v13, a45
	v_accvgpr_read_b32 v14, a46
	v_accvgpr_read_b32 v15, a47
	v_div_fixup_f32 v172, v130, v131, 1.0
	s_barrier
	s_and_saveexec_b64 s[60:61], s[4:5]
	s_cbranch_execz .LBB0_1090
	v_accvgpr_read_b32 v133, a252
	v_mul_f32_e32 v130, v133, v224
	v_mul_f32_e32 v131, v112, v130
	v_mul_f32_e32 v132, v113, v130
	ds_write2st64_b32 v139, v131, v132 offset1:1
	v_mul_f32_e32 v131, v114, v130
	v_mul_f32_e32 v132, v115, v130
	ds_write2st64_b32 v139, v131, v132 offset0:2 offset1:3
	v_mul_f32_e32 v131, v116, v130
	v_mul_f32_e32 v132, v117, v130
	ds_write2st64_b32 v139, v131, v132 offset0:4 offset1:5
	v_mul_f32_e32 v131, v118, v130
	v_mul_f32_e32 v132, v119, v130
	ds_write2st64_b32 v139, v131, v132 offset0:6 offset1:7
	v_mul_f32_e32 v131, v120, v130
	v_mul_f32_e32 v132, v121, v130
	ds_write2st64_b32 v139, v131, v132 offset0:8 offset1:9
	v_mul_f32_e32 v131, v122, v130
	v_mul_f32_e32 v132, v123, v130
	ds_write2st64_b32 v139, v131, v132 offset0:10 offset1:11
	v_mul_f32_e32 v131, v124, v130
	v_mul_f32_e32 v132, v125, v130
	ds_write2st64_b32 v139, v131, v132 offset0:12 offset1:13
	v_mul_f32_e32 v131, v126, v130
	v_mul_f32_e32 v132, v127, v130
	ds_write2st64_b32 v139, v131, v132 offset0:14 offset1:15
	v_mul_f32_e32 v131, v96, v130
	v_mul_f32_e32 v132, v97, v130
	ds_write2st64_b32 v139, v131, v132 offset0:16 offset1:17
	v_mul_f32_e32 v131, v98, v130
	v_mul_f32_e32 v132, v99, v130
	ds_write2st64_b32 v139, v131, v132 offset0:18 offset1:19
	v_mul_f32_e32 v131, v100, v130
	v_mul_f32_e32 v132, v101, v130
	ds_write2st64_b32 v139, v131, v132 offset0:20 offset1:21
	v_mul_f32_e32 v131, v102, v130
	v_mul_f32_e32 v132, v103, v130
	ds_write2st64_b32 v139, v131, v132 offset0:22 offset1:23
	v_mul_f32_e32 v131, v104, v130
	v_mul_f32_e32 v132, v105, v130
	ds_write2st64_b32 v139, v131, v132 offset0:24 offset1:25
	v_mul_f32_e32 v131, v106, v130
	v_mul_f32_e32 v132, v107, v130
	ds_write2st64_b32 v139, v131, v132 offset0:26 offset1:27
	v_mul_f32_e32 v131, v108, v130
	v_mul_f32_e32 v132, v109, v130
	ds_write2st64_b32 v139, v131, v132 offset0:28 offset1:29
	v_mul_f32_e32 v131, v110, v130
	v_mul_f32_e32 v132, v111, v130
	ds_write2st64_b32 v139, v131, v132 offset0:30 offset1:31
	v_mul_f32_e32 v131, v80, v130
	v_mul_f32_e32 v132, v81, v130
	ds_write2st64_b32 v139, v131, v132 offset0:32 offset1:33
	v_mul_f32_e32 v131, v82, v130
	v_mul_f32_e32 v132, v83, v130
	ds_write2st64_b32 v139, v131, v132 offset0:34 offset1:35
	v_mul_f32_e32 v131, v84, v130
	v_mul_f32_e32 v132, v85, v130
	ds_write2st64_b32 v139, v131, v132 offset0:36 offset1:37
	v_mul_f32_e32 v131, v86, v130
	v_mul_f32_e32 v132, v87, v130
	ds_write2st64_b32 v139, v131, v132 offset0:38 offset1:39
	v_mul_f32_e32 v131, v88, v130
	v_mul_f32_e32 v132, v89, v130
	ds_write2st64_b32 v139, v131, v132 offset0:40 offset1:41
	v_mul_f32_e32 v131, v90, v130
	v_mul_f32_e32 v132, v91, v130
	ds_write2st64_b32 v139, v131, v132 offset0:42 offset1:43
	v_mul_f32_e32 v131, v92, v130
	v_mul_f32_e32 v132, v93, v130
	ds_write2st64_b32 v139, v131, v132 offset0:44 offset1:45
	v_mul_f32_e32 v131, v94, v130
	v_mul_f32_e32 v132, v95, v130
	ds_write2st64_b32 v139, v131, v132 offset0:46 offset1:47
	v_mul_f32_e32 v131, v64, v130
	v_mul_f32_e32 v132, v65, v130
	ds_write2st64_b32 v139, v131, v132 offset0:48 offset1:49
	v_mul_f32_e32 v131, v66, v130
	v_mul_f32_e32 v132, v67, v130
	ds_write2st64_b32 v139, v131, v132 offset0:50 offset1:51
	v_mul_f32_e32 v131, v68, v130
	v_mul_f32_e32 v132, v69, v130
	ds_write2st64_b32 v139, v131, v132 offset0:52 offset1:53
	v_mul_f32_e32 v131, v70, v130
	v_mul_f32_e32 v132, v71, v130
	ds_write2st64_b32 v139, v131, v132 offset0:54 offset1:55
	v_mul_f32_e32 v131, v72, v130
	v_mul_f32_e32 v132, v73, v130
	ds_write2st64_b32 v139, v131, v132 offset0:56 offset1:57
	v_mul_f32_e32 v131, v74, v130
	v_mul_f32_e32 v132, v75, v130
	ds_write2st64_b32 v139, v131, v132 offset0:58 offset1:59
	v_mul_f32_e32 v131, v76, v130
	v_mul_f32_e32 v132, v77, v130
	ds_write2st64_b32 v139, v131, v132 offset0:60 offset1:61
	v_mul_f32_e32 v131, v78, v130
	v_mul_f32_e32 v130, v79, v130
	ds_write2st64_b32 v139, v131, v130 offset0:62 offset1:63
	v_mul_f32_e32 v130, v133, v172
	v_mul_f32_e32 v131, v48, v130
	v_mul_f32_e32 v132, v49, v130
	ds_write2st64_b32 v254, v131, v132 offset1:1
	v_mul_f32_e32 v131, v50, v130
	v_mul_f32_e32 v132, v51, v130
	ds_write2st64_b32 v254, v131, v132 offset0:2 offset1:3
	v_mul_f32_e32 v131, v52, v130
	v_mul_f32_e32 v132, v53, v130
	ds_write2st64_b32 v254, v131, v132 offset0:4 offset1:5
	v_mul_f32_e32 v131, v54, v130
	v_mul_f32_e32 v132, v55, v130
	ds_write2st64_b32 v254, v131, v132 offset0:6 offset1:7
	v_mul_f32_e32 v131, v56, v130
	v_mul_f32_e32 v132, v57, v130
	ds_write2st64_b32 v254, v131, v132 offset0:8 offset1:9
	v_mul_f32_e32 v131, v58, v130
	v_mul_f32_e32 v132, v59, v130
	ds_write2st64_b32 v254, v131, v132 offset0:10 offset1:11
	v_mul_f32_e32 v131, v60, v130
	v_mul_f32_e32 v132, v61, v130
	ds_write2st64_b32 v254, v131, v132 offset0:12 offset1:13
	v_mul_f32_e32 v131, v62, v130
	v_mul_f32_e32 v132, v63, v130
	ds_write2st64_b32 v254, v131, v132 offset0:14 offset1:15
	v_mul_f32_e32 v131, v32, v130
	v_mul_f32_e32 v132, v33, v130
	ds_write2st64_b32 v254, v131, v132 offset0:16 offset1:17
	v_mul_f32_e32 v131, v34, v130
	v_mul_f32_e32 v132, v35, v130
	ds_write2st64_b32 v254, v131, v132 offset0:18 offset1:19
	v_mul_f32_e32 v131, v36, v130
	v_mul_f32_e32 v132, v37, v130
	ds_write2st64_b32 v254, v131, v132 offset0:20 offset1:21
	v_mul_f32_e32 v131, v38, v130
	v_mul_f32_e32 v132, v39, v130
	ds_write2st64_b32 v254, v131, v132 offset0:22 offset1:23
	v_mul_f32_e32 v131, v40, v130
	v_mul_f32_e32 v132, v41, v130
	ds_write2st64_b32 v254, v131, v132 offset0:24 offset1:25
	v_mul_f32_e32 v131, v42, v130
	v_mul_f32_e32 v132, v43, v130
	ds_write2st64_b32 v254, v131, v132 offset0:26 offset1:27
	v_mul_f32_e32 v131, v44, v130
	v_mul_f32_e32 v132, v45, v130
	ds_write2st64_b32 v254, v131, v132 offset0:28 offset1:29
	v_mul_f32_e32 v131, v46, v130
	v_mul_f32_e32 v132, v47, v130
	ds_write2st64_b32 v254, v131, v132 offset0:30 offset1:31
	v_mul_f32_e32 v131, v16, v130
	v_mul_f32_e32 v132, v17, v130
	ds_write2st64_b32 v254, v131, v132 offset0:32 offset1:33
	v_mul_f32_e32 v131, v18, v130
	v_mul_f32_e32 v132, v19, v130
	ds_write2st64_b32 v254, v131, v132 offset0:34 offset1:35
	v_mul_f32_e32 v131, v20, v130
	v_mul_f32_e32 v132, v21, v130
	ds_write2st64_b32 v254, v131, v132 offset0:36 offset1:37
	v_mul_f32_e32 v131, v22, v130
	v_mul_f32_e32 v132, v23, v130
	ds_write2st64_b32 v254, v131, v132 offset0:38 offset1:39
	v_mul_f32_e32 v131, v24, v130
	v_mul_f32_e32 v132, v25, v130
	ds_write2st64_b32 v254, v131, v132 offset0:40 offset1:41
	v_mul_f32_e32 v131, v26, v130
	v_mul_f32_e32 v132, v27, v130
	ds_write2st64_b32 v254, v131, v132 offset0:42 offset1:43
	v_mul_f32_e32 v131, v28, v130
	v_mul_f32_e32 v132, v29, v130
	ds_write2st64_b32 v254, v131, v132 offset0:44 offset1:45
	v_mul_f32_e32 v131, v30, v130
	v_mul_f32_e32 v132, v31, v130
	ds_write2st64_b32 v254, v131, v132 offset0:46 offset1:47
	v_mul_f32_e32 v131, v0, v130
	v_mul_f32_e32 v132, v1, v130
	ds_write2st64_b32 v254, v131, v132 offset0:48 offset1:49
	v_mul_f32_e32 v131, v2, v130
	v_mul_f32_e32 v132, v3, v130
	ds_write2st64_b32 v254, v131, v132 offset0:50 offset1:51
	v_mul_f32_e32 v131, v4, v130
	v_mul_f32_e32 v132, v5, v130
	ds_write2st64_b32 v254, v131, v132 offset0:52 offset1:53
	v_mul_f32_e32 v131, v6, v130
	v_mul_f32_e32 v132, v7, v130
	ds_write2st64_b32 v254, v131, v132 offset0:54 offset1:55
	v_mul_f32_e32 v131, v8, v130
	v_mul_f32_e32 v132, v9, v130
	ds_write2st64_b32 v254, v131, v132 offset0:56 offset1:57
	v_mul_f32_e32 v131, v10, v130
	v_mul_f32_e32 v132, v11, v130
	ds_write2st64_b32 v254, v131, v132 offset0:58 offset1:59
	v_mul_f32_e32 v131, v12, v130
	v_mul_f32_e32 v132, v13, v130
	ds_write2st64_b32 v254, v131, v132 offset0:60 offset1:61
	v_mul_f32_e32 v131, v14, v130
	v_mul_f32_e32 v130, v15, v130
	ds_write2st64_b32 v254, v131, v130 offset0:62 offset1:63

.LBB0_2270:
	s_lshl_b64 s[58:59], s[4:5], 10
	s_lshl_b64 s[64:65], s[4:5], 11
	v_mov_b32_e32 v243, v149
	s_lshl_b32 s4, s68, 7
	v_lshl_add_u64 v[0:1], s[62:63], 0, v[242:243]
	v_mov_b32_e32 v245, v149
	v_mov_b32_e32 v247, v149
	s_add_u32 s70, s62, s4
	v_lshl_add_u64 v[0:1], v[0:1], 0, v[244:245]
	v_lshl_add_u64 v[2:3], s[62:63], 0, v[246:247]
	s_addc_u32 s71, s63, 0
	v_lshl_add_u64 v[2:3], v[2:3], 0, v[244:245]
	global_load_dwordx4 v[32:35], v[0:1], off
	global_load_dwordx4 v[36:39], v[2:3], off
	v_lshl_add_u64 v[0:1], s[70:71], 0, v[242:243]
	v_lshl_add_u64 v[0:1], v[0:1], 0, v[244:245]
	v_lshl_add_u64 v[2:3], s[70:71], 0, v[246:247]
	v_lshl_add_u64 v[2:3], v[2:3], 0, v[244:245]
	global_load_dwordx4 v[40:43], v[0:1], off
	global_load_dwordx4 v[44:47], v[2:3], off
	v_accvgpr_read_b32 v0, a209
	v_mul_u32_u24_e32 v0, s68, v0
	v_lshlrev_b32_e32 v64, 1, v0
	v_mov_b32_e32 v65, v149
	v_mul_u32_u24_e32 v2, s68, v152
	v_lshl_add_u64 v[0:1], s[60:61], 0, v[64:65]
	v_lshlrev_b32_e32 v66, 1, v2
	v_mov_b32_e32 v67, v149
	v_lshl_add_u64 v[0:1], v[0:1], 0, v[244:245]
	v_lshl_add_u64 v[2:3], s[60:61], 0, v[66:67]
	v_lshl_add_u64 v[2:3], v[2:3], 0, v[244:245]
	global_load_dwordx4 v[48:51], v[0:1], off
	global_load_dwordx4 v[52:55], v[2:3], off
	v_mul_u32_u24_e32 v0, s68, v153
	v_lshlrev_b32_e32 v68, 1, v0
	v_mov_b32_e32 v69, v149
	v_mul_u32_u24_e32 v2, s68, v160
	v_lshl_add_u64 v[0:1], s[60:61], 0, v[68:69]
	v_lshlrev_b32_e32 v70, 1, v2
	v_mov_b32_e32 v71, v149
	v_lshl_add_u64 v[0:1], v[0:1], 0, v[244:245]
	v_lshl_add_u64 v[2:3], s[60:61], 0, v[70:71]
	v_lshl_add_u64 v[2:3], v[2:3], 0, v[244:245]
	global_load_dwordx4 v[56:59], v[0:1], off
	global_load_dwordx4 v[60:63], v[2:3], off
	v_mov_b32_e32 v251, v149
	v_lshl_add_u64 v[0:1], v[164:165], 0, s[64:65]
	v_lshl_add_u64 v[2:3], v[0:1], 0, v[148:149]
	v_lshl_add_u64 v[0:1], v[0:1], 0, v[250:251]
	global_load_dwordx4 v[28:31], v[2:3], off
	global_load_dwordx4 v[24:27], v[2:3], off offset:32
	global_load_dwordx4 v[20:23], v[2:3], off offset:64
	global_load_dwordx4 v[16:19], v[2:3], off offset:96
	global_load_dwordx4 v[12:15], v[0:1], off
	global_load_dwordx4 v[8:11], v[0:1], off offset:32
	global_load_dwordx4 v[4:7], v[0:1], off offset:64
	s_nop 0
	global_load_dwordx4 v[0:3], v[0:1], off offset:96
	v_lshl_add_u64 v[82:83], s[62:63], 0, v[146:147]
	v_lshl_add_u64 v[84:85], s[62:63], 0, v[166:167]
	v_lshl_add_u64 v[86:87], v[82:83], 0, s[4:5]
	v_lshl_add_u64 v[88:89], v[84:85], 0, s[4:5]
	s_add_i32 s4, s67, 1
	s_add_u32 s60, s60, 0x80
	v_mov_b32_e32 v80, 0
	s_addc_u32 s61, s61, 0
	v_accvgpr_write_b32 a31, 0
	v_accvgpr_write_b32 a30, 0
	v_accvgpr_write_b32 a29, 0
	v_accvgpr_write_b32 a28, 0
	v_accvgpr_write_b32 a27, 0
	v_accvgpr_write_b32 a26, 0
	v_accvgpr_write_b32 a25, 0
	v_accvgpr_write_b32 a24, 0
	v_accvgpr_write_b32 a23, 0
	v_accvgpr_write_b32 a22, 0
	v_lshl_add_u64 v[90:91], s[60:61], 0, v[64:65]
	v_lshl_add_u64 v[92:93], s[60:61], 0, v[66:67]
	v_lshl_add_u64 v[94:95], s[60:61], 0, v[68:69]
	v_lshl_add_u64 v[96:97], s[60:61], 0, v[70:71]
	v_accvgpr_write_b32 a21, 0
	v_accvgpr_write_b32 a20, 0
	v_accvgpr_write_b32 a19, 0
	v_accvgpr_write_b32 a18, 0
	v_accvgpr_write_b32 a17, 0
	v_accvgpr_write_b32 a16, 0
	v_accvgpr_write_b32 a111, 0
	v_accvgpr_write_b32 a110, 0
	v_accvgpr_write_b32 a109, 0
	v_accvgpr_write_b32 a108, 0
	v_accvgpr_write_b32 a107, 0
	v_accvgpr_write_b32 a106, 0
	v_accvgpr_write_b32 a105, 0
	v_accvgpr_write_b32 a104, 0
	v_accvgpr_write_b32 a103, 0
	v_accvgpr_write_b32 a102, 0
	v_accvgpr_write_b32 a101, 0
	v_accvgpr_write_b32 a100, 0
	v_accvgpr_write_b32 a99, 0
	v_accvgpr_write_b32 a98, 0
	v_accvgpr_write_b32 a97, 0
	v_accvgpr_write_b32 a96, 0
	v_accvgpr_write_b32 a143, 0
	v_accvgpr_write_b32 a142, 0
	v_accvgpr_write_b32 a141, 0
	v_accvgpr_write_b32 a140, 0
	v_accvgpr_write_b32 a139, 0
	v_accvgpr_write_b32 a138, 0
	v_accvgpr_write_b32 a137, 0
	v_accvgpr_write_b32 a136, 0
	v_accvgpr_write_b32 a135, 0
	v_accvgpr_write_b32 a134, 0
	v_accvgpr_write_b32 a133, 0
	v_accvgpr_write_b32 a132, 0
	v_accvgpr_write_b32 a131, 0
	v_accvgpr_write_b32 a130, 0
	v_accvgpr_write_b32 a129, 0
	v_accvgpr_write_b32 a128, 0
	v_accvgpr_write_b32 a63, 0
	v_accvgpr_write_b32 a62, 0
	v_accvgpr_write_b32 a61, 0
	v_accvgpr_write_b32 a60, 0
	v_accvgpr_write_b32 a59, 0
	v_accvgpr_write_b32 a58, 0
	v_accvgpr_write_b32 a57, 0
	v_accvgpr_write_b32 a56, 0
	v_accvgpr_write_b32 a55, 0
	v_accvgpr_write_b32 a54, 0
	v_accvgpr_write_b32 a53, 0
	v_accvgpr_write_b32 a52, 0
	v_accvgpr_write_b32 a51, 0
	v_accvgpr_write_b32 a50, 0
	v_accvgpr_write_b32 a49, 0
	v_accvgpr_write_b32 a48, 0
	v_accvgpr_write_b32 a95, 0
	v_accvgpr_write_b32 a94, 0
	v_accvgpr_write_b32 a93, 0
	v_accvgpr_write_b32 a92, 0
	v_accvgpr_write_b32 a91, 0
	v_accvgpr_write_b32 a90, 0
	v_accvgpr_write_b32 a89, 0
	v_accvgpr_write_b32 a88, 0
	v_accvgpr_write_b32 a87, 0
	v_accvgpr_write_b32 a86, 0
	v_accvgpr_write_b32 a85, 0
	v_accvgpr_write_b32 a84, 0
	v_accvgpr_write_b32 a83, 0
	v_accvgpr_write_b32 a82, 0
	v_accvgpr_write_b32 a81, 0
	v_accvgpr_write_b32 a80, 0
	v_accvgpr_write_b32 a47, 0
	v_accvgpr_write_b32 a46, 0
	v_accvgpr_write_b32 a45, 0
	v_accvgpr_write_b32 a44, 0
	v_accvgpr_write_b32 a43, 0
	v_accvgpr_write_b32 a42, 0
	v_accvgpr_write_b32 a41, 0
	v_accvgpr_write_b32 a40, 0
	v_accvgpr_write_b32 a39, 0
	v_accvgpr_write_b32 a38, 0
	v_accvgpr_write_b32 a37, 0
	v_accvgpr_write_b32 a36, 0
	v_accvgpr_write_b32 a35, 0
	v_accvgpr_write_b32 a34, 0
	v_accvgpr_write_b32 a33, 0
	v_accvgpr_write_b32 a32, 0
	v_accvgpr_write_b32 a127, 0
	v_accvgpr_write_b32 a126, 0
	v_accvgpr_write_b32 a125, 0
	v_accvgpr_write_b32 a124, 0
	v_accvgpr_write_b32 a123, 0
	v_accvgpr_write_b32 a122, 0
	v_accvgpr_write_b32 a121, 0
	v_accvgpr_write_b32 a120, 0
	v_accvgpr_write_b32 a119, 0
	v_accvgpr_write_b32 a118, 0
	v_accvgpr_write_b32 a117, 0
	v_accvgpr_write_b32 a116, 0
	v_accvgpr_write_b32 a115, 0
	v_accvgpr_write_b32 a114, 0
	v_accvgpr_write_b32 a113, 0
	v_accvgpr_write_b32 a112, 0
	v_accvgpr_write_b32 a79, 0
	v_accvgpr_write_b32 a78, 0
	v_accvgpr_write_b32 a77, 0
	v_accvgpr_write_b32 a76, 0
	v_accvgpr_write_b32 a75, 0
	v_accvgpr_write_b32 a74, 0
	v_accvgpr_write_b32 a73, 0
	v_accvgpr_write_b32 a72, 0
	v_accvgpr_write_b32 a71, 0
	v_accvgpr_write_b32 a70, 0
	v_accvgpr_write_b32 a69, 0
	v_accvgpr_write_b32 a68, 0
	v_accvgpr_write_b32 a67, 0
	v_accvgpr_write_b32 a66, 0
	v_accvgpr_write_b32 a65, 0
	v_accvgpr_write_b32 a64, 0
	s_mov_b32 s60, 0
	v_mov_b32_e32 v81, v80
	s_waitcnt vmcnt(15)
	ds_write_b128 v129, v[32:35]
	s_waitcnt vmcnt(14)
	ds_write_b128 v135, v[36:39]
	s_waitcnt vmcnt(13)
	ds_write_b128 v129, v[40:43] offset:9216
	s_waitcnt vmcnt(12)
	ds_write_b128 v135, v[44:47] offset:9216
	s_waitcnt vmcnt(11)
	ds_write_b128 v129, v[48:51] offset:36864
	s_waitcnt vmcnt(10)
	ds_write_b128 v135, v[52:55] offset:36864
	s_waitcnt vmcnt(9)
	ds_write_b128 v161, v[56:59] offset:36864
	s_waitcnt vmcnt(8)
	ds_write_b128 v162, v[60:63] offset:36864
	v_accvgpr_write_b32 a160, 0
	v_mov_b32_e32 v48, 0
	v_accvgpr_write_b32 a161, 0
	v_mov_b32_e32 v49, 0
	v_accvgpr_write_b32 a162, 0
	v_mov_b32_e32 v50, 0
	v_accvgpr_write_b32 a163, 0
	v_mov_b32_e32 v51, 0
	v_accvgpr_write_b32 a164, 0
	v_mov_b32_e32 v52, 0
	v_accvgpr_write_b32 a165, 0
	v_mov_b32_e32 v53, 0
	v_accvgpr_write_b32 a166, 0
	v_mov_b32_e32 v54, 0
	v_accvgpr_write_b32 a167, 0
	v_mov_b32_e32 v55, 0
	v_accvgpr_write_b32 a168, 0
	v_mov_b32_e32 v56, 0
	v_accvgpr_write_b32 a169, 0
	v_mov_b32_e32 v57, 0
	v_accvgpr_write_b32 a170, 0
	v_mov_b32_e32 v58, 0
	v_accvgpr_write_b32 a171, 0
	v_mov_b32_e32 v59, 0
	v_accvgpr_write_b32 a172, 0
	v_mov_b32_e32 v60, 0
	v_accvgpr_write_b32 a173, 0
	v_mov_b32_e32 v61, 0
	v_accvgpr_write_b32 a174, 0
	v_mov_b32_e32 v62, 0
	v_accvgpr_write_b32 a175, 0
	v_mov_b32_e32 v63, 0
	v_accvgpr_write_b32 a176, 0
	v_mov_b32_e32 v116, 0
	v_accvgpr_write_b32 a177, 0
	v_mov_b32_e32 v117, 0
	v_accvgpr_write_b32 a178, 0
	v_mov_b32_e32 v118, 0
	v_accvgpr_write_b32 a179, 0
	v_mov_b32_e32 v119, 0
	v_accvgpr_write_b32 a180, 0
	v_mov_b32_e32 v120, 0
	v_accvgpr_write_b32 a181, 0
	v_mov_b32_e32 v121, 0
	v_accvgpr_write_b32 a182, 0
	v_mov_b32_e32 v122, 0
	v_accvgpr_write_b32 a183, 0
	v_mov_b32_e32 v123, 0
	v_accvgpr_write_b32 a184, 0
	v_mov_b32_e32 v124, 0
	v_accvgpr_write_b32 a185, 0
	v_mov_b32_e32 v125, 0
	v_accvgpr_write_b32 a186, 0
	v_mov_b32_e32 v126, 0
	v_accvgpr_write_b32 a187, 0
	v_mov_b32_e32 v127, 0
	v_accvgpr_write_b32 a188, 0
	v_mov_b32_e32 v130, 0
	v_accvgpr_write_b32 a189, 0
	v_mov_b32_e32 v131, 0
	v_accvgpr_write_b32 a190, 0
	v_mov_b32_e32 v132, 0
	v_accvgpr_write_b32 a191, 0
	v_mov_b32_e32 v133, 0
	v_accvgpr_read_b32 v32, a0
	v_accvgpr_read_b32 v33, a0
	v_accvgpr_read_b32 v34, a0
	v_accvgpr_read_b32 v35, a0
	v_accvgpr_read_b32 v36, a0
	v_accvgpr_read_b32 v37, a0
	v_accvgpr_read_b32 v38, a0
	v_accvgpr_read_b32 v39, a0
	v_accvgpr_read_b32 v40, a0
	v_accvgpr_read_b32 v41, a0
	v_accvgpr_read_b32 v42, a0
	v_accvgpr_read_b32 v43, a0
	v_accvgpr_read_b32 v44, a0
	v_accvgpr_read_b32 v45, a0
	v_accvgpr_read_b32 v46, a0
	v_accvgpr_read_b32 v47, a0
	v_mbcnt_lo_u32_b32 v235, -1, 0
	v_mbcnt_hi_u32_b32 v235, -1, v235
	v_lshlrev_b32_e32 v235, 4, v235
	v_add_u32_e32 v235, 0xd800, v235
	s_waitcnt lgkmcnt(0)
	ds_write_b128 v235, a[160:163]
	ds_write_b128 v235, a[160:163] offset:1024
	ds_write_b128 v235, a[160:163] offset:2048
	ds_write_b128 v235, a[160:163] offset:3072
	ds_write_b128 v235, a[160:163] offset:4096
	ds_write_b128 v235, a[160:163] offset:5120
	ds_write_b128 v235, a[160:163] offset:6144
	ds_write_b128 v235, a[160:163] offset:7168
	ds_write_b128 v235, a[160:163] offset:8192
	s_waitcnt lgkmcnt(0)
	ds_write_b128 v235, a[160:163] offset:9216
	ds_write_b128 v235, a[160:163] offset:10240
	ds_write_b128 v235, a[160:163] offset:11264
	ds_write_b128 v235, a[160:163] offset:12288
	ds_write_b128 v235, a[160:163] offset:13312
	ds_write_b128 v235, a[160:163] offset:14336
	ds_write_b128 v235, a[160:163] offset:15360
	ds_write_b128 v235, a[160:163] offset:16384
	ds_write_b128 v235, a[160:163] offset:17408
.LBB0_2271:
	s_and_b32 s61, s60, 1
	s_xor_b32 s62, s61, 1
	s_mulk_i32 s61, 0x4800
	s_mulk_i32 s62, 0x4800
	v_add_u32_e32 v233, s61, v128
	v_add_u32_e32 v234, s62, v150
	s_waitcnt vmcnt(0) lgkmcnt(0)
	s_barrier
	ds_read_b128 a[144:147], v233
	ds_read_b128 a[148:151], v233 offset:32
	ds_read_b128 a[152:155], v233 offset:64
	ds_read_b128 a[156:159], v233 offset:96
	s_waitcnt lgkmcnt(3)
	v_mfma_f32_32x32x16_bf16 v[184:199], a[144:147], v[28:31], v[32:47]
	s_cmp_eq_u32 s60, 0
	s_cselect_b32 s32, 0x9000, s61
	v_add3_u32 v220, s32, v151, v134
	v_add3_u32 v221, s32, v156, v134
	v_mfma_f32_32x32x16_bf16 v[168:183], a[144:147], v[12:15], v[32:47]
	v_add3_u32 v222, s32, v157, v134
	v_add3_u32 v232, s32, v158, v134
	ds_write_b128 v220, v[140:143] offset:36864
	ds_read_b128 a[144:147], v233 offset:4608
	s_waitcnt lgkmcnt(4)
	v_mfma_f32_32x32x16_bf16 v[184:199], a[148:151], v[24:27], v[184:199]
	ds_write_b128 v221, v[216:219] offset:36864
	ds_write_b128 v222, v[224:227] offset:36864
	ds_write_b128 v232, v[228:231] offset:36864
	v_lshl_add_u64 v[98:99], v[82:83], 0, v[154:155]
	v_mfma_f32_32x32x16_bf16 v[168:183], a[148:151], v[8:11], v[168:183]
	global_load_dwordx4 v[64:67], v[98:99], off
	v_lshl_add_u64 v[98:99], v[84:85], 0, v[154:155]
	global_load_dwordx4 v[68:71], v[98:99], off
	ds_read_b128 a[148:151], v233 offset:4640
	s_waitcnt lgkmcnt(7)
	v_mfma_f32_32x32x16_bf16 v[184:199], a[152:155], v[20:23], v[184:199]
	v_lshl_add_u64 v[98:99], v[86:87], 0, v[154:155]
	global_load_dwordx4 v[72:75], v[98:99], off
	v_lshl_add_u64 v[98:99], v[88:89], 0, v[154:155]
	v_mfma_f32_32x32x16_bf16 v[168:183], a[152:155], v[4:7], v[168:183]
	global_load_dwordx4 v[76:79], v[98:99], off
	v_accvgpr_write_b32 a160, v48
	v_accvgpr_write_b32 a161, v49
	v_accvgpr_write_b32 a162, v50
	ds_read_b128 a[152:155], v233 offset:4672
	s_waitcnt lgkmcnt(7)
	v_mfma_f32_32x32x16_bf16 v[184:199], a[156:159], v[16:19], v[184:199]
	v_accvgpr_write_b32 a163, v51
	v_accvgpr_write_b32 a164, v52
	v_accvgpr_write_b32 a165, v53
	v_mfma_f32_32x32x16_bf16 v[168:183], a[156:159], v[0:3], v[168:183]
	v_accvgpr_write_b32 a166, v54
	v_accvgpr_write_b32 a167, v55
	v_accvgpr_write_b32 a168, v56
	ds_read_b128 a[156:159], v233 offset:4704
	s_waitcnt lgkmcnt(6)
	v_mfma_f32_32x32x16_bf16 v[200:215], a[144:147], v[28:31], v[32:47]
	v_accvgpr_write_b32 a169, v57
	v_accvgpr_write_b32 a170, v58
	v_accvgpr_write_b32 a171, v59
	v_accvgpr_write_b32 a172, v60
	v_mfma_f32_32x32x16_bf16 v[100:115], a[144:147], v[12:15], v[32:47]
	v_accvgpr_write_b32 a173, v61
	v_accvgpr_write_b32 a174, v62
	v_accvgpr_write_b32 a175, v63
	s_waitcnt lgkmcnt(2)
	v_mfma_f32_32x32x16_bf16 v[200:215], a[148:151], v[24:27], v[200:215]
	v_accvgpr_write_b32 a176, v116
	v_accvgpr_write_b32 a177, v117
	v_accvgpr_write_b32 a178, v118
	v_accvgpr_write_b32 a179, v119
	v_mfma_f32_32x32x16_bf16 v[100:115], a[148:151], v[8:11], v[100:115]
	v_accvgpr_write_b32 a180, v120
	v_accvgpr_write_b32 a181, v121
	v_accvgpr_write_b32 a182, v122
	s_waitcnt lgkmcnt(1)
	v_mfma_f32_32x32x16_bf16 v[200:215], a[152:155], v[20:23], v[200:215]
	v_accvgpr_write_b32 a183, v123
	v_accvgpr_write_b32 a184, v124
	v_accvgpr_write_b32 a185, v125
	v_mfma_f32_32x32x16_bf16 v[100:115], a[152:155], v[4:7], v[100:115]
	v_accvgpr_write_b32 a186, v126
	v_accvgpr_write_b32 a187, v127
	v_accvgpr_write_b32 a188, v130
	v_accvgpr_write_b32 a189, v131
	s_waitcnt lgkmcnt(0)
	v_mfma_f32_32x32x16_bf16 v[200:215], a[156:159], v[16:19], v[200:215]
	v_accvgpr_write_b32 a190, v132
	v_accvgpr_write_b32 a191, v133
	v_lshl_add_u64 v[82:83], v[82:83], 0, s[54:55]
	v_mfma_f32_32x32x16_bf16 v[100:115], a[156:159], v[0:3], v[100:115]
	v_lshl_add_u64 v[84:85], v[84:85], 0, s[54:55]
	v_lshl_add_u64 v[86:87], v[86:87], 0, s[54:55]
	v_lshl_add_u64 v[88:89], v[88:89], 0, s[54:55]
	ds_read_b128 a[144:147], v234 offset:36864
	ds_read_b128 a[148:151], v234 offset:36896
	ds_read_b128 a[152:155], v234 offset:36928
	ds_read_b128 a[156:159], v234 offset:36960
	s_waitcnt lgkmcnt(3)
	v_mfma_f32_32x32x16_bf16 a[128:143], a[144:147], a[160:163], a[128:143]
	v_exp_f32_e32 v184, v184
	v_exp_f32_e32 v185, v185
	v_exp_f32_e32 v186, v186
	v_mfma_f32_32x32x16_bf16 a[112:127], a[144:147], a[176:179], a[112:127]
	v_exp_f32_e32 v187, v187
	v_exp_f32_e32 v188, v188
	v_exp_f32_e32 v189, v189
	v_exp_f32_e32 v190, v190
	ds_read_b128 a[144:147], v234 offset:41472
	s_waitcnt lgkmcnt(3)
	v_mfma_f32_32x32x16_bf16 a[128:143], a[148:151], a[164:167], a[128:143]
	v_exp_f32_e32 v191, v191
	v_exp_f32_e32 v192, v192
	v_exp_f32_e32 v193, v193
	v_exp_f32_e32 v194, v194
	v_mfma_f32_32x32x16_bf16 a[112:127], a[148:151], a[180:183], a[112:127]
	v_exp_f32_e32 v195, v195
	v_exp_f32_e32 v196, v196
	v_exp_f32_e32 v197, v197
	v_exp_f32_e32 v198, v198
	ds_read_b128 a[148:151], v234 offset:41504
	s_waitcnt lgkmcnt(3)
	v_mfma_f32_32x32x16_bf16 a[128:143], a[152:155], a[168:171], a[128:143]
	v_exp_f32_e32 v199, v199
	v_pk_add_f32 v[136:137], v[184:185], v[186:187]
	v_pk_add_f32 v[136:137], v[136:137], v[188:189]
	v_pk_add_f32 v[136:137], v[136:137], v[190:191]
	v_mfma_f32_32x32x16_bf16 a[112:127], a[152:155], a[184:187], a[112:127]
	v_pk_add_f32 v[136:137], v[136:137], v[192:193]
	v_pk_add_f32 v[136:137], v[136:137], v[194:195]
	v_pk_add_f32 v[136:137], v[136:137], v[196:197]
	v_pk_add_f32 v[136:137], v[136:137], v[198:199]
	ds_read_b128 a[152:155], v234 offset:41536
	s_waitcnt lgkmcnt(3)
	v_mfma_f32_32x32x16_bf16 a[128:143], a[156:159], a[172:175], a[128:143]
	v_cvt_pk_bf16_f32 v48, v184, v185
	v_cvt_pk_bf16_f32 v49, v186, v187
	v_cvt_pk_bf16_f32 v50, v188, v189
	v_cvt_pk_bf16_f32 v51, v190, v191
	v_cvt_pk_bf16_f32 v52, v192, v193
	v_cvt_pk_bf16_f32 v53, v194, v195
	v_cvt_pk_bf16_f32 v54, v196, v197
	v_mfma_f32_32x32x16_bf16 a[112:127], a[156:159], a[188:191], a[112:127]
	v_cvt_pk_bf16_f32 v55, v198, v199
	v_add3_u32 v220, s62, v151, v134
	v_add3_u32 v221, s62, v156, v134
	s_waitcnt vmcnt(3)
	ds_write_b128 v220, v[64:67]
	s_waitcnt vmcnt(2)
	ds_write_b128 v221, v[68:71]
	s_waitcnt vmcnt(1)
	ds_read_b128 a[156:159], v234 offset:41568
	s_waitcnt lgkmcnt(5)
	v_mfma_f32_32x32x16_bf16 a[48:63], a[144:147], a[160:163], a[48:63]
	ds_write_b128 v220, v[72:75] offset:9216
	s_waitcnt vmcnt(0)
	ds_write_b128 v221, v[76:79] offset:9216
	v_lshl_add_u64 v[98:99], v[90:91], 0, v[154:155]
	global_load_dwordx4 v[140:143], v[98:99], off
	v_lshl_add_u64 v[98:99], v[92:93], 0, v[154:155]
	global_load_dwordx4 v[216:219], v[98:99], off
	v_lshl_add_u64 v[98:99], v[94:95], 0, v[154:155]
	v_mfma_f32_32x32x16_bf16 a[64:79], a[144:147], a[176:179], a[64:79]
	global_load_dwordx4 v[224:227], v[98:99], off
	v_lshl_add_u64 v[98:99], v[96:97], 0, v[154:155]
	global_load_dwordx4 v[228:231], v[98:99], off
	v_lshl_add_u64 v[90:91], v[90:91], 0, s[56:57]
	v_lshl_add_u64 v[92:93], v[92:93], 0, s[56:57]
	v_lshl_add_u64 v[94:95], v[94:95], 0, s[56:57]
	v_lshl_add_u64 v[96:97], v[96:97], 0, s[56:57]
	ds_read_b128 a[144:147], v234 offset:46080
	s_waitcnt lgkmcnt(7)
	v_mfma_f32_32x32x16_bf16 a[48:63], a[148:151], a[164:167], a[48:63]
	v_exp_f32_e32 v168, v168
	v_exp_f32_e32 v169, v169
	v_exp_f32_e32 v170, v170
	v_exp_f32_e32 v171, v171
	v_mfma_f32_32x32x16_bf16 a[64:79], a[148:151], a[180:183], a[64:79]
	v_exp_f32_e32 v172, v172
	v_exp_f32_e32 v173, v173
	v_exp_f32_e32 v174, v174
	v_exp_f32_e32 v175, v175
	ds_read_b128 a[148:151], v234 offset:46112
	s_waitcnt lgkmcnt(7)
	v_mfma_f32_32x32x16_bf16 a[48:63], a[152:155], a[168:171], a[48:63]
	v_exp_f32_e32 v176, v176
	v_exp_f32_e32 v177, v177
	v_exp_f32_e32 v178, v178
	v_mfma_f32_32x32x16_bf16 a[64:79], a[152:155], a[184:187], a[64:79]
	v_exp_f32_e32 v179, v179
	v_exp_f32_e32 v180, v180
	v_exp_f32_e32 v181, v181
	v_exp_f32_e32 v182, v182
	ds_read_b128 a[152:155], v234 offset:46144
	s_waitcnt lgkmcnt(5)
	v_mfma_f32_32x32x16_bf16 a[48:63], a[156:159], a[172:175], a[48:63]
	v_exp_f32_e32 v183, v183
	v_pk_add_f32 v[144:145], v[168:169], v[170:171]
	v_pk_add_f32 v[144:145], v[144:145], v[172:173]
	v_pk_add_f32 v[144:145], v[144:145], v[174:175]
	v_mfma_f32_32x32x16_bf16 a[64:79], a[156:159], a[188:191], a[64:79]
	v_pk_add_f32 v[144:145], v[144:145], v[176:177]
	v_pk_add_f32 v[144:145], v[144:145], v[178:179]
	v_pk_add_f32 v[144:145], v[144:145], v[180:181]
	v_pk_add_f32 v[144:145], v[144:145], v[182:183]
	v_cvt_pk_bf16_f32 v116, v168, v169
	ds_read_b128 a[156:159], v234 offset:46176
	s_waitcnt lgkmcnt(3)
	v_mfma_f32_32x32x16_bf16 a[80:95], a[144:147], a[160:163], a[80:95]
	v_cvt_pk_bf16_f32 v117, v170, v171
	v_cvt_pk_bf16_f32 v118, v172, v173
	v_cvt_pk_bf16_f32 v119, v174, v175
	v_cvt_pk_bf16_f32 v120, v176, v177
	v_cvt_pk_bf16_f32 v121, v178, v179
	v_cvt_pk_bf16_f32 v122, v180, v181
	v_cvt_pk_bf16_f32 v123, v182, v183
	v_mfma_f32_32x32x16_bf16 a[96:111], a[144:147], a[176:179], a[96:111]
	v_exp_f32_e32 v200, v200
	v_exp_f32_e32 v201, v201
	v_exp_f32_e32 v202, v202
	v_exp_f32_e32 v203, v203
	ds_read_b128 a[144:147], v234 offset:50688
	s_waitcnt lgkmcnt(3)
	v_mfma_f32_32x32x16_bf16 a[80:95], a[148:151], a[164:167], a[80:95]
	v_exp_f32_e32 v204, v204
	v_exp_f32_e32 v205, v205
	v_exp_f32_e32 v206, v206
	v_exp_f32_e32 v207, v207
	v_mfma_f32_32x32x16_bf16 a[96:111], a[148:151], a[180:183], a[96:111]
	v_exp_f32_e32 v208, v208
	v_exp_f32_e32 v209, v209
	v_exp_f32_e32 v210, v210
	ds_read_b128 a[148:151], v234 offset:50720
	s_waitcnt lgkmcnt(3)
	v_mfma_f32_32x32x16_bf16 a[80:95], a[152:155], a[168:171], a[80:95]
	v_exp_f32_e32 v211, v211
	v_exp_f32_e32 v212, v212
	v_exp_f32_e32 v213, v213
	v_exp_f32_e32 v214, v214
	v_mfma_f32_32x32x16_bf16 a[96:111], a[152:155], a[184:187], a[96:111]
	v_exp_f32_e32 v215, v215
	v_pk_add_f32 v[136:137], v[136:137], v[200:201]
	v_pk_add_f32 v[136:137], v[136:137], v[202:203]
	v_pk_add_f32 v[136:137], v[136:137], v[204:205]
	ds_read_b128 a[152:155], v234 offset:50752
	s_waitcnt lgkmcnt(3)
	v_mfma_f32_32x32x16_bf16 a[80:95], a[156:159], a[172:175], a[80:95]
	v_pk_add_f32 v[136:137], v[136:137], v[206:207]
	v_pk_add_f32 v[136:137], v[136:137], v[208:209]
	v_pk_add_f32 v[136:137], v[136:137], v[210:211]
	v_pk_add_f32 v[136:137], v[136:137], v[212:213]
	v_mfma_f32_32x32x16_bf16 a[96:111], a[156:159], a[188:191], a[96:111]
	v_pk_add_f32 v[136:137], v[136:137], v[214:215]
	v_cvt_pk_bf16_f32 v56, v200, v201
	v_cvt_pk_bf16_f32 v57, v202, v203
	v_cvt_pk_bf16_f32 v58, v204, v205
	v_cvt_pk_bf16_f32 v59, v206, v207
	v_cvt_pk_bf16_f32 v60, v208, v209
	v_cvt_pk_bf16_f32 v61, v210, v211
	ds_read_b128 a[156:159], v234 offset:50784
	s_waitcnt lgkmcnt(3)
	v_mfma_f32_32x32x16_bf16 a[32:47], a[144:147], a[160:163], a[32:47]
	v_cvt_pk_bf16_f32 v62, v212, v213
	v_cvt_pk_bf16_f32 v63, v214, v215
	v_add_f32_e32 v235, v136, v137
	v_add_f32_e32 v81, v81, v235
	v_exp_f32_e32 v100, v100
	v_exp_f32_e32 v101, v101
	v_mfma_f32_32x32x16_bf16 a[16:31], a[144:147], a[176:179], a[16:31]
	v_exp_f32_e32 v102, v102
	v_exp_f32_e32 v103, v103
	v_exp_f32_e32 v104, v104
	s_waitcnt lgkmcnt(2)
	v_mfma_f32_32x32x16_bf16 a[32:47], a[148:151], a[164:167], a[32:47]
	v_exp_f32_e32 v105, v105
	v_exp_f32_e32 v106, v106
	v_exp_f32_e32 v107, v107
	v_exp_f32_e32 v108, v108
	v_mfma_f32_32x32x16_bf16 a[16:31], a[148:151], a[180:183], a[16:31]
	v_exp_f32_e32 v109, v109
	v_exp_f32_e32 v110, v110
	v_exp_f32_e32 v111, v111
	v_exp_f32_e32 v112, v112
	s_waitcnt lgkmcnt(1)
	v_mfma_f32_32x32x16_bf16 a[32:47], a[152:155], a[168:171], a[32:47]
	v_exp_f32_e32 v113, v113
	v_exp_f32_e32 v114, v114
	v_exp_f32_e32 v115, v115
	v_pk_add_f32 v[144:145], v[144:145], v[100:101]
	v_mfma_f32_32x32x16_bf16 a[16:31], a[152:155], a[184:187], a[16:31]
	v_pk_add_f32 v[144:145], v[144:145], v[102:103]
	v_pk_add_f32 v[144:145], v[144:145], v[104:105]
	v_pk_add_f32 v[144:145], v[144:145], v[106:107]
	v_pk_add_f32 v[144:145], v[144:145], v[108:109]
	s_waitcnt lgkmcnt(0)
	v_mfma_f32_32x32x16_bf16 a[32:47], a[156:159], a[172:175], a[32:47]
	v_pk_add_f32 v[144:145], v[144:145], v[110:111]
	v_pk_add_f32 v[144:145], v[144:145], v[112:113]
	v_pk_add_f32 v[144:145], v[144:145], v[114:115]
	v_cvt_pk_bf16_f32 v124, v100, v101
	v_cvt_pk_bf16_f32 v125, v102, v103
	v_mfma_f32_32x32x16_bf16 a[16:31], a[156:159], a[188:191], a[16:31]
	v_cvt_pk_bf16_f32 v126, v104, v105
	v_cvt_pk_bf16_f32 v127, v106, v107
	v_cvt_pk_bf16_f32 v130, v108, v109
	v_cvt_pk_bf16_f32 v131, v110, v111
	v_cvt_pk_bf16_f32 v132, v112, v113
	v_cvt_pk_bf16_f32 v133, v114, v115
	v_add_f32_e32 v235, v144, v145
	v_add_f32_e32 v80, v80, v235
	s_add_i32 s60, s60, 1
	s_cmp_eq_u32 s4, s60
	s_cbranch_scc0 .LBB0_2271
	s_waitcnt vmcnt(0) lgkmcnt(0)
	s_barrier
	v_add3_u32 v220, s62, v151, v134
	v_add3_u32 v221, s62, v156, v134
	v_add3_u32 v222, s62, v157, v134
	v_add3_u32 v232, s62, v158, v134
	ds_write_b128 v220, v[140:143] offset:36864
	ds_write_b128 v221, v[216:219] offset:36864
	ds_write_b128 v222, v[224:227] offset:36864
	ds_write_b128 v232, v[228:231] offset:36864
	v_add_u32_e32 v234, s61, v150
	ds_read_b128 a[144:147], v234 offset:36864
	ds_read_b128 a[148:151], v234 offset:36896
	ds_read_b128 a[152:155], v234 offset:36928
	ds_read_b128 a[156:159], v234 offset:36960
	s_waitcnt lgkmcnt(3)
	v_mfma_f32_32x32x16_bf16 a[128:143], a[144:147], v[48:51], a[128:143]
	v_mfma_f32_32x32x16_bf16 a[112:127], a[144:147], v[116:119], a[112:127]
	ds_read_b128 a[144:147], v234 offset:41472
	s_waitcnt lgkmcnt(3)
	v_mfma_f32_32x32x16_bf16 a[128:143], a[148:151], v[52:55], a[128:143]
	v_mfma_f32_32x32x16_bf16 a[112:127], a[148:151], v[120:123], a[112:127]
	ds_read_b128 a[148:151], v234 offset:41504
	s_waitcnt lgkmcnt(3)
	v_mfma_f32_32x32x16_bf16 a[128:143], a[152:155], v[56:59], a[128:143]
	v_mfma_f32_32x32x16_bf16 a[112:127], a[152:155], v[124:127], a[112:127]
	ds_read_b128 a[152:155], v234 offset:41536
	s_waitcnt lgkmcnt(3)
	v_mfma_f32_32x32x16_bf16 a[128:143], a[156:159], v[60:63], a[128:143]
	v_mfma_f32_32x32x16_bf16 a[112:127], a[156:159], v[130:133], a[112:127]
	ds_read_b128 a[156:159], v234 offset:41568
	s_waitcnt lgkmcnt(3)
	v_mfma_f32_32x32x16_bf16 a[48:63], a[144:147], v[48:51], a[48:63]
	v_mfma_f32_32x32x16_bf16 a[64:79], a[144:147], v[116:119], a[64:79]
	ds_read_b128 a[144:147], v234 offset:46080
	s_waitcnt lgkmcnt(3)
	v_mfma_f32_32x32x16_bf16 a[48:63], a[148:151], v[52:55], a[48:63]
	v_mfma_f32_32x32x16_bf16 a[64:79], a[148:151], v[120:123], a[64:79]
	ds_read_b128 a[148:151], v234 offset:46112
	s_waitcnt lgkmcnt(3)
	v_mfma_f32_32x32x16_bf16 a[48:63], a[152:155], v[56:59], a[48:63]
	v_mfma_f32_32x32x16_bf16 a[64:79], a[152:155], v[124:127], a[64:79]
	ds_read_b128 a[152:155], v234 offset:46144
	s_waitcnt lgkmcnt(3)
	v_mfma_f32_32x32x16_bf16 a[48:63], a[156:159], v[60:63], a[48:63]
	v_mfma_f32_32x32x16_bf16 a[64:79], a[156:159], v[130:133], a[64:79]
	ds_read_b128 a[156:159], v234 offset:46176
	s_waitcnt lgkmcnt(3)
	v_mfma_f32_32x32x16_bf16 a[80:95], a[144:147], v[48:51], a[80:95]
	v_mfma_f32_32x32x16_bf16 a[96:111], a[144:147], v[116:119], a[96:111]
	ds_read_b128 a[144:147], v234 offset:50688
	s_waitcnt lgkmcnt(3)
	v_mfma_f32_32x32x16_bf16 a[80:95], a[148:151], v[52:55], a[80:95]
	v_mfma_f32_32x32x16_bf16 a[96:111], a[148:151], v[120:123], a[96:111]
	ds_read_b128 a[148:151], v234 offset:50720
	s_waitcnt lgkmcnt(3)
	v_mfma_f32_32x32x16_bf16 a[80:95], a[152:155], v[56:59], a[80:95]
	v_mfma_f32_32x32x16_bf16 a[96:111], a[152:155], v[124:127], a[96:111]
	ds_read_b128 a[152:155], v234 offset:50752
	s_waitcnt lgkmcnt(3)
	v_mfma_f32_32x32x16_bf16 a[80:95], a[156:159], v[60:63], a[80:95]
	v_mfma_f32_32x32x16_bf16 a[96:111], a[156:159], v[130:133], a[96:111]
	ds_read_b128 a[156:159], v234 offset:50784
	s_waitcnt lgkmcnt(3)
	v_mfma_f32_32x32x16_bf16 a[32:47], a[144:147], v[48:51], a[32:47]
	v_mfma_f32_32x32x16_bf16 a[16:31], a[144:147], v[116:119], a[16:31]
	s_waitcnt lgkmcnt(2)
	v_mfma_f32_32x32x16_bf16 a[32:47], a[148:151], v[52:55], a[32:47]
	v_mfma_f32_32x32x16_bf16 a[16:31], a[148:151], v[120:123], a[16:31]
	s_waitcnt lgkmcnt(1)
	v_mfma_f32_32x32x16_bf16 a[32:47], a[152:155], v[56:59], a[32:47]
	v_mfma_f32_32x32x16_bf16 a[16:31], a[152:155], v[124:127], a[16:31]
	s_waitcnt lgkmcnt(0)
	v_mfma_f32_32x32x16_bf16 a[32:47], a[156:159], v[60:63], a[32:47]
	v_mfma_f32_32x32x16_bf16 a[16:31], a[156:159], v[130:133], a[16:31]
	s_bitcmp1_b32 s4, 0
	s_cselect_b32 s4, 0x4800, 0
	v_add_u32_e32 v48, s4, v128
	s_waitcnt lgkmcnt(0)
	s_barrier
	ds_read_b128 v[32:35], v48
	ds_read_b128 v[36:39], v48 offset:32
	s_waitcnt lgkmcnt(1)
	v_mfma_f32_32x32x16_bf16 a[186:201], v[32:35], v[28:31], a[0:15]
	v_add_u32_e32 v83, s4, v150
	v_mfma_f32_32x32x16_bf16 a[144:159], v[32:35], v[12:15], a[0:15]
	s_waitcnt lgkmcnt(0)
	v_mfma_f32_32x32x16_bf16 a[186:201], v[36:39], v[24:27], a[186:201]
	v_mfma_f32_32x32x16_bf16 a[144:159], v[36:39], v[8:11], a[144:159]
	ds_read_b128 v[32:35], v48 offset:64
	ds_read_b128 v[36:39], v48 offset:96
	s_waitcnt lgkmcnt(1)
	v_mfma_f32_32x32x16_bf16 a[186:201], v[32:35], v[20:23], a[186:201]
	s_waitcnt lgkmcnt(0)
	v_mfma_f32_32x32x16_bf16 a[186:201], v[36:39], v[16:19], a[186:201]
	v_mfma_f32_32x32x16_bf16 a[144:159], v[32:35], v[4:7], a[144:159]
	ds_read_b128 v[32:35], v48 offset:4608
	ds_read_b128 v[40:43], v48 offset:4640
	ds_read_b128 v[44:47], v48 offset:4672
	ds_read_b128 v[48:51], v48 offset:4704
	s_nop 6
	v_accvgpr_read_b32 v52, a186
	v_accvgpr_read_b32 v53, a187
	v_accvgpr_read_b32 v54, a188
	v_exp_f32_e32 v52, v52
	v_exp_f32_e32 v53, v53
	s_waitcnt lgkmcnt(3)
	v_mfma_f32_32x32x16_bf16 a[172:187], v[32:35], v[28:31], a[0:15]
	v_accvgpr_read_b32 v28, a189
	v_exp_f32_e32 v55, v28
	v_accvgpr_read_b32 v28, a190
	v_exp_f32_e32 v56, v28
	v_accvgpr_read_b32 v28, a191
	v_exp_f32_e32 v54, v54
	v_exp_f32_e32 v57, v28
	s_waitcnt lgkmcnt(2)
	v_mfma_f32_32x32x16_bf16 a[172:187], v[40:43], v[24:27], a[172:187]
	v_accvgpr_read_b32 v24, a192
	v_exp_f32_e32 v58, v24
	v_accvgpr_read_b32 v24, a193
	v_exp_f32_e32 v59, v24
	v_accvgpr_read_b32 v24, a194
	v_exp_f32_e32 v60, v24
	v_accvgpr_read_b32 v24, a195
	s_waitcnt lgkmcnt(1)
	v_mfma_f32_32x32x16_bf16 a[172:187], v[44:47], v[20:23], a[172:187]
	v_accvgpr_read_b32 v20, a196
	v_exp_f32_e32 v62, v20
	v_accvgpr_read_b32 v20, a197
	v_exp_f32_e32 v63, v20
	v_accvgpr_read_b32 v20, a198
	v_exp_f32_e32 v64, v20
	v_exp_f32_e32 v61, v24
	s_waitcnt lgkmcnt(0)
	v_mfma_f32_32x32x16_bf16 a[172:187], v[48:51], v[16:19], a[172:187]
	v_accvgpr_read_b32 v16, a199
	v_exp_f32_e32 v65, v16
	v_accvgpr_read_b32 v16, a200
	v_exp_f32_e32 v66, v16
	v_accvgpr_read_b32 v16, a201
	v_exp_f32_e32 v67, v16
	ds_read_b128 v[28:31], v83 offset:36928
	v_mfma_f32_32x32x16_bf16 a[144:159], v[36:39], v[0:3], a[144:159]
	s_nop 3
	v_accvgpr_read_b32 v16, a172
	v_exp_f32_e32 v36, v16
	v_accvgpr_read_b32 v16, a173
	v_exp_f32_e32 v37, v16
	v_accvgpr_read_b32 v16, a174
	v_exp_f32_e32 v38, v16
	v_accvgpr_read_b32 v16, a175
	v_mfma_f32_32x32x16_bf16 a[160:175], v[32:35], v[12:15], a[0:15]
	v_exp_f32_e32 v39, v16
	v_accvgpr_read_b32 v16, a144
	v_accvgpr_read_b32 v12, a176
	v_exp_f32_e32 v68, v12
	v_accvgpr_read_b32 v12, a177
	v_accvgpr_read_b32 v20, a157
	v_exp_f32_e32 v69, v12
	v_mfma_f32_32x32x16_bf16 a[160:175], v[40:43], v[8:11], a[160:175]
	v_accvgpr_read_b32 v12, a178
	v_exp_f32_e32 v84, v20
	v_accvgpr_read_b32 v20, a158
	v_exp_f32_e32 v70, v12
	v_accvgpr_read_b32 v12, a179
	v_exp_f32_e32 v85, v20
	v_accvgpr_read_b32 v20, a159
	v_mfma_f32_32x32x16_bf16 a[160:175], v[44:47], v[4:7], a[160:175]
	v_exp_f32_e32 v40, v12
	v_cvt_pk_bf16_f32 v12, v52, v53
	v_cvt_pk_bf16_f32 v13, v54, v55
	v_cvt_pk_bf16_f32 v14, v56, v57
	v_cvt_pk_bf16_f32 v15, v58, v59
	v_exp_f32_e32 v86, v20
	ds_read_b128 v[20:23], v83 offset:36896
	v_mfma_f32_32x32x16_bf16 a[160:175], v[48:51], v[0:3], a[160:175]
	v_exp_f32_e32 v49, v16
	v_accvgpr_read_b32 v16, a145
	v_exp_f32_e32 v50, v16
	v_accvgpr_read_b32 v16, a146
	v_exp_f32_e32 v51, v16
	v_accvgpr_read_b32 v16, a147
	v_exp_f32_e32 v71, v16
	v_accvgpr_read_b32 v16, a148
	v_exp_f32_e32 v72, v16
	v_accvgpr_read_b32 v16, a149
	v_exp_f32_e32 v73, v16
	v_accvgpr_read_b32 v16, a150
	v_exp_f32_e32 v74, v16
	v_accvgpr_read_b32 v16, a151
	v_exp_f32_e32 v75, v16
	v_accvgpr_read_b32 v16, a152
	v_exp_f32_e32 v76, v16
	v_accvgpr_read_b32 v16, a153
	v_exp_f32_e32 v77, v16
	v_accvgpr_read_b32 v16, a154
	v_exp_f32_e32 v78, v16
	v_accvgpr_read_b32 v16, a155
	v_exp_f32_e32 v79, v16
	v_accvgpr_read_b32 v16, a156
	v_exp_f32_e32 v82, v16
	ds_read_b128 v[16:19], v83 offset:36864
	v_accvgpr_read_b32 v24, a160
	v_exp_f32_e32 v87, v24
	v_accvgpr_read_b32 v24, a161
	v_exp_f32_e32 v88, v24
	v_cvt_pk_bf16_f32 v24, v49, v50
	v_cvt_pk_bf16_f32 v25, v51, v71
	v_cvt_pk_bf16_f32 v26, v72, v73
	v_cvt_pk_bf16_f32 v27, v74, v75
	s_waitcnt lgkmcnt(0)
	v_mfma_f32_32x32x16_bf16 a[144:159], v[16:19], v[12:15], a[128:143]
	v_accvgpr_read_b32 v8, a180
	v_exp_f32_e32 v41, v8
	v_accvgpr_read_b32 v8, a181
	v_exp_f32_e32 v42, v8
	v_accvgpr_read_b32 v8, a182
	v_exp_f32_e32 v43, v8
	v_cvt_pk_bf16_f32 v8, v60, v61
	v_mfma_f32_32x32x16_bf16 a[128:143], v[16:19], v[24:27], a[112:127]
	v_accvgpr_read_b32 v16, a162
	v_exp_f32_e32 v89, v16
	v_accvgpr_read_b32 v16, a163
	v_exp_f32_e32 v90, v16
	v_accvgpr_read_b32 v16, a164
	v_exp_f32_e32 v91, v16
	v_accvgpr_read_b32 v16, a165
	v_cvt_pk_bf16_f32 v9, v62, v63
	v_cvt_pk_bf16_f32 v10, v64, v65
	v_cvt_pk_bf16_f32 v11, v66, v67
	v_exp_f32_e32 v92, v16
	v_cvt_pk_bf16_f32 v16, v76, v77
	v_cvt_pk_bf16_f32 v17, v78, v79
	v_cvt_pk_bf16_f32 v18, v82, v84
	v_cvt_pk_bf16_f32 v19, v85, v86
	v_mfma_f32_32x32x16_bf16 a[144:159], v[20:23], v[8:11], a[144:159]
	v_accvgpr_read_b32 v32, a166
	v_accvgpr_read_b32 v4, a183
	v_exp_f32_e32 v93, v32
	v_exp_f32_e32 v44, v4
	v_accvgpr_read_b32 v4, a184
	v_exp_f32_e32 v45, v4
	v_accvgpr_read_b32 v4, a185
	v_mfma_f32_32x32x16_bf16 a[128:143], v[20:23], v[16:19], a[128:143]
	v_accvgpr_read_b32 v20, a167
	v_exp_f32_e32 v94, v20
	v_accvgpr_read_b32 v32, a169
	v_exp_f32_e32 v46, v4
	v_accvgpr_read_b32 v4, a186
	v_exp_f32_e32 v96, v32
	v_accvgpr_read_b32 v32, a170
	v_exp_f32_e32 v47, v4
	v_cvt_pk_bf16_f32 v4, v36, v37
	v_cvt_pk_bf16_f32 v5, v38, v39
	v_cvt_pk_bf16_f32 v6, v68, v69
	v_cvt_pk_bf16_f32 v7, v70, v40
	v_accvgpr_read_b32 v20, a168
	v_exp_f32_e32 v97, v32
	v_cvt_pk_bf16_f32 v32, v87, v88
	v_cvt_pk_bf16_f32 v33, v89, v90
	v_cvt_pk_bf16_f32 v34, v91, v92
	v_cvt_pk_bf16_f32 v35, v93, v94
	v_exp_f32_e32 v95, v20
	ds_read_b128 v[20:23], v83 offset:36960
	v_mfma_f32_32x32x16_bf16 a[144:159], v[28:31], v[4:7], a[144:159]
	v_accvgpr_read_b32 v0, a187
	v_exp_f32_e32 v48, v0
	v_cvt_pk_bf16_f32 v0, v41, v42
	v_cvt_pk_bf16_f32 v1, v43, v44
	v_cvt_pk_bf16_f32 v2, v45, v46
	v_cvt_pk_bf16_f32 v3, v47, v48
	v_cvt_pk_bf16_f32 v130, v95, v96
	v_mfma_f32_32x32x16_bf16 a[128:143], v[28:31], v[32:35], a[128:143]
	v_accvgpr_read_b32 v28, a171
	v_exp_f32_e32 v98, v28
	v_accvgpr_read_b32 v28, a172
	v_exp_f32_e32 v99, v28
	v_accvgpr_read_b32 v28, a173
	v_exp_f32_e32 v100, v28
	v_accvgpr_read_b32 v28, a174
	v_exp_f32_e32 v101, v28
	v_accvgpr_read_b32 v28, a175
	v_exp_f32_e32 v102, v28
	v_cvt_pk_bf16_f32 v131, v97, v98
	v_cvt_pk_bf16_f32 v132, v99, v100
	s_waitcnt lgkmcnt(0)
	v_mfma_f32_32x32x16_bf16 a[144:159], v[20:23], v[0:3], a[144:159]
	v_cvt_pk_bf16_f32 v133, v101, v102
	s_nop 1
	v_mfma_f32_32x32x16_bf16 a[128:143], v[20:23], v[130:133], a[128:143]
	ds_read_b128 v[20:23], v83 offset:41472
	ds_read_b128 v[28:31], v83 offset:41504
	s_nop 5
	v_accvgpr_read_b32 v112, a144
	v_accvgpr_read_b32 v113, a145
	v_accvgpr_read_b32 v114, a146
	v_accvgpr_read_b32 v115, a147
	s_waitcnt lgkmcnt(1)
	v_mfma_f32_32x32x16_bf16 a[112:127], v[20:23], v[12:15], a[48:63]
	v_accvgpr_read_b32 v116, a148
	v_accvgpr_read_b32 v117, a149
	v_accvgpr_read_b32 v118, a150
	v_accvgpr_read_b32 v119, a151
	v_accvgpr_read_b32 v120, a152
	v_accvgpr_read_b32 v121, a153
	v_accvgpr_read_b32 v122, a154
	v_mfma_f32_32x32x16_bf16 a[48:63], v[20:23], v[24:27], a[64:79]
	v_accvgpr_read_b32 v123, a155
	v_accvgpr_read_b32 v124, a156
	v_accvgpr_read_b32 v125, a157
	v_accvgpr_read_b32 v126, a158
	v_accvgpr_read_b32 v127, a159
	s_waitcnt lgkmcnt(0)
	v_mfma_f32_32x32x16_bf16 a[112:127], v[28:31], v[8:11], a[112:127]
	v_mfma_f32_32x32x16_bf16 a[48:63], v[28:31], v[16:19], a[48:63]
	ds_read_b128 v[20:23], v83 offset:41536
	ds_read_b128 v[28:31], v83 offset:41568
	s_waitcnt lgkmcnt(1)
	v_mfma_f32_32x32x16_bf16 a[112:127], v[20:23], v[4:7], a[112:127]
	v_mfma_f32_32x32x16_bf16 a[48:63], v[20:23], v[32:35], a[48:63]
	s_waitcnt lgkmcnt(0)
	v_mfma_f32_32x32x16_bf16 a[112:127], v[28:31], v[0:3], a[112:127]
	v_mfma_f32_32x32x16_bf16 a[48:63], v[28:31], v[130:133], a[48:63]
	ds_read_b128 v[20:23], v83 offset:46080
	ds_read_b128 v[28:31], v83 offset:46112
	s_waitcnt lgkmcnt(1)
	v_mfma_f32_32x32x16_bf16 a[64:79], v[20:23], v[12:15], a[80:95]
	v_mfma_f32_32x32x16_bf16 a[80:95], v[20:23], v[24:27], a[96:111]
	ds_read_b128 v[20:23], v83 offset:46144
	s_waitcnt lgkmcnt(1)
	v_mfma_f32_32x32x16_bf16 a[64:79], v[28:31], v[8:11], a[64:79]
	v_mfma_f32_32x32x16_bf16 a[80:95], v[28:31], v[16:19], a[80:95]
	v_add_f32_e32 v28, 0, v52
	v_add_f32_e32 v28, v53, v28
	v_add_f32_e32 v28, v54, v28
	v_add_f32_e32 v28, v55, v28
	v_add_f32_e32 v52, v56, v28
	v_add_f32_e32 v52, v57, v52
	v_add_f32_e32 v52, v58, v52
	v_add_f32_e32 v52, v59, v52
	v_add_f32_e32 v52, v60, v52
	v_add_f32_e32 v52, v61, v52
	v_add_f32_e32 v52, v62, v52
	v_add_f32_e32 v52, v63, v52
	ds_read_b128 v[28:31], v83 offset:46176
	s_waitcnt lgkmcnt(1)
	v_mfma_f32_32x32x16_bf16 a[64:79], v[20:23], v[4:7], a[64:79]
	v_mfma_f32_32x32x16_bf16 a[80:95], v[20:23], v[32:35], a[80:95]
	v_add_f32_e32 v20, v64, v52
	v_add_f32_e32 v20, v65, v20
	v_add_f32_e32 v20, v66, v20
	v_add_f32_e32 v20, v67, v20
	v_add_f32_e32 v20, v36, v20
	v_add_f32_e32 v20, v37, v20
	v_add_f32_e32 v20, v38, v20
	v_add_f32_e32 v20, v39, v20
	v_add_f32_e32 v20, v68, v20
	v_add_f32_e32 v20, v69, v20
	v_add_f32_e32 v20, v70, v20
	v_add_f32_e32 v20, v40, v20
	v_add_f32_e32 v36, v41, v20
	ds_read_b128 v[20:23], v83 offset:50688
	s_waitcnt lgkmcnt(1)
	v_mfma_f32_32x32x16_bf16 a[64:79], v[28:31], v[0:3], a[64:79]
	v_mfma_f32_32x32x16_bf16 a[80:95], v[28:31], v[130:133], a[80:95]
	v_add_f32_e32 v28, v42, v36
	v_add_f32_e32 v28, v43, v28
	v_add_f32_e32 v28, v44, v28
	v_add_f32_e32 v28, v45, v28
	v_add_f32_e32 v28, v46, v28
	v_add_f32_e32 v36, v47, v28
	ds_read_b128 v[28:31], v83 offset:50720
	s_waitcnt lgkmcnt(1)
	v_mfma_f32_32x32x16_bf16 a[96:111], v[20:23], v[12:15], a[32:47]
	v_add_f32_e32 v12, v48, v36
	v_add_f32_e32 v136, v81, v12
	v_add_f32_e32 v12, 0, v49
	v_add_f32_e32 v12, v50, v12
	v_add_f32_e32 v12, v51, v12
	v_add_f32_e32 v12, v71, v12
	v_add_f32_e32 v12, v72, v12
	v_add_f32_e32 v12, v73, v12
	v_add_f32_e32 v12, v74, v12
	v_add_f32_e32 v12, v75, v12
	v_add_f32_e32 v12, v76, v12
	v_add_f32_e32 v12, v77, v12
	v_add_f32_e32 v12, v78, v12
	v_add_f32_e32 v12, v79, v12
	s_waitcnt lgkmcnt(0)
	v_mfma_f32_32x32x16_bf16 a[96:111], v[28:31], v[8:11], a[96:111]
	v_add_f32_e32 v8, v82, v12
	v_add_f32_e32 v8, v84, v8
	v_add_f32_e32 v8, v85, v8
	v_add_f32_e32 v8, v86, v8
	v_add_f32_e32 v8, v87, v8
	v_add_f32_e32 v12, v88, v8
	ds_read_b128 v[8:11], v83 offset:50752
	v_mfma_f32_32x32x16_bf16 a[32:47], v[20:23], v[24:27], a[16:31]
	v_add_f32_e32 v12, v89, v12
	v_add_f32_e32 v12, v90, v12
	v_add_f32_e32 v12, v91, v12
	v_add_f32_e32 v12, v92, v12
	v_add_f32_e32 v12, v93, v12
	v_accvgpr_read_b32 v48, a128
	v_accvgpr_read_b32 v49, a129
	v_mfma_f32_32x32x16_bf16 a[32:47], v[28:31], v[16:19], a[32:47]
	v_add_f32_e32 v16, v94, v12
	ds_read_b128 v[12:15], v83 offset:50784
	v_accvgpr_read_b32 v50, a130
	v_accvgpr_read_b32 v51, a131
	v_accvgpr_read_b32 v52, a132
	v_accvgpr_read_b32 v53, a133
	v_accvgpr_read_b32 v54, a134
	s_waitcnt lgkmcnt(1)
	v_mfma_f32_32x32x16_bf16 a[96:111], v[8:11], v[4:7], a[96:111]
	v_add_f32_e32 v4, v95, v16
	v_add_f32_e32 v4, v96, v4
	v_add_f32_e32 v4, v97, v4
	v_add_f32_e32 v4, v98, v4
	v_add_f32_e32 v4, v99, v4
	v_add_f32_e32 v4, v100, v4
	v_add_f32_e32 v4, v101, v4
	v_add_f32_e32 v4, v102, v4
	v_add_f32_e32 v137, v80, v4
	ds_bpermute_b32 v4, v159, v136
	v_mfma_f32_32x32x16_bf16 a[32:47], v[8:11], v[32:35], a[32:47]
	v_accvgpr_read_b32 v96, a112
	v_accvgpr_read_b32 v32, a48
	v_accvgpr_read_b32 v95, a79
	s_waitcnt lgkmcnt(0)
	v_add_f32_e32 v136, v136, v4
	v_div_scale_f32 v140, s[60:61], v136, v136, 1.0
	v_rcp_f32_e32 v141, v140
	v_mfma_f32_32x32x16_bf16 a[32:47], v[12:15], v[130:133], a[32:47]
	ds_bpermute_b32 v131, v159, v137
	v_accvgpr_read_b32 v16, a80
	v_fma_f32 v130, -v140, v141, 1.0
	v_fmac_f32_e32 v141, v130, v141
	v_div_scale_f32 v130, vcc, 1.0, v136, 1.0
	v_mul_f32_e32 v132, v130, v141
	v_fma_f32 v133, -v140, v132, v130
	s_waitcnt lgkmcnt(0)
	v_add_f32_e32 v131, v137, v131
	v_fmac_f32_e32 v132, v133, v141
	v_div_scale_f32 v133, s[60:61], v131, v131, 1.0
	v_rcp_f32_e32 v137, v133
	v_mfma_f32_32x32x16_bf16 a[96:111], v[12:15], v[0:3], a[96:111]
	v_fma_f32 v130, -v140, v132, v130
	v_div_fmas_f32 v130, v130, v141, v132
	v_div_fixup_f32 v222, v130, v136, 1.0
	v_fma_f32 v130, -v133, v137, 1.0
	v_fmac_f32_e32 v137, v130, v137
	v_div_scale_f32 v130, vcc, 1.0, v131, 1.0
	v_mul_f32_e32 v132, v130, v137
	v_fma_f32 v136, -v133, v132, v130
	v_fmac_f32_e32 v132, v136, v137
	v_fma_f32 v130, -v133, v132, v130
	v_accvgpr_read_b32 v0, a32
	s_nop 0
	v_accvgpr_read_b32 v64, a96
	v_div_fmas_f32 v130, v130, v137, v132
	v_accvgpr_read_b32 v55, a135
	v_accvgpr_read_b32 v56, a136
	v_accvgpr_read_b32 v57, a137
	v_accvgpr_read_b32 v58, a138
	v_accvgpr_read_b32 v59, a139
	v_accvgpr_read_b32 v60, a140
	v_accvgpr_read_b32 v61, a141
	v_accvgpr_read_b32 v62, a142
	v_accvgpr_read_b32 v63, a143
	v_accvgpr_read_b32 v97, a113
	v_accvgpr_read_b32 v98, a114
	v_accvgpr_read_b32 v99, a115
	v_accvgpr_read_b32 v100, a116
	v_accvgpr_read_b32 v101, a117
	v_accvgpr_read_b32 v102, a118
	v_accvgpr_read_b32 v103, a119
	v_accvgpr_read_b32 v104, a120
	v_accvgpr_read_b32 v105, a121
	v_accvgpr_read_b32 v106, a122
	v_accvgpr_read_b32 v107, a123
	v_accvgpr_read_b32 v108, a124
	v_accvgpr_read_b32 v109, a125
	v_accvgpr_read_b32 v110, a126
	v_accvgpr_read_b32 v111, a127
	v_accvgpr_read_b32 v33, a49
	v_accvgpr_read_b32 v34, a50
	v_accvgpr_read_b32 v35, a51
	v_accvgpr_read_b32 v36, a52
	v_accvgpr_read_b32 v37, a53
	v_accvgpr_read_b32 v38, a54
	v_accvgpr_read_b32 v39, a55
	v_accvgpr_read_b32 v40, a56
	v_accvgpr_read_b32 v41, a57
	v_accvgpr_read_b32 v42, a58
	v_accvgpr_read_b32 v43, a59
	v_accvgpr_read_b32 v44, a60
	v_accvgpr_read_b32 v45, a61
	v_accvgpr_read_b32 v46, a62
	v_accvgpr_read_b32 v47, a63
	v_accvgpr_read_b32 v94, a78
	v_accvgpr_read_b32 v93, a77
	v_accvgpr_read_b32 v92, a76
	v_accvgpr_read_b32 v91, a75
	v_accvgpr_read_b32 v90, a74
	v_accvgpr_read_b32 v89, a73
	v_accvgpr_read_b32 v88, a72
	v_accvgpr_read_b32 v87, a71
	v_accvgpr_read_b32 v86, a70
	v_accvgpr_read_b32 v85, a69
	v_accvgpr_read_b32 v84, a68
	v_accvgpr_read_b32 v83, a67
	v_accvgpr_read_b32 v82, a66
	v_accvgpr_read_b32 v81, a65
	v_accvgpr_read_b32 v80, a64
	v_accvgpr_read_b32 v17, a81
	v_accvgpr_read_b32 v18, a82
	v_accvgpr_read_b32 v19, a83
	v_accvgpr_read_b32 v20, a84
	v_accvgpr_read_b32 v21, a85
	v_accvgpr_read_b32 v22, a86
	v_accvgpr_read_b32 v23, a87
	v_accvgpr_read_b32 v24, a88
	v_accvgpr_read_b32 v25, a89
	v_accvgpr_read_b32 v26, a90
	v_accvgpr_read_b32 v27, a91
	v_accvgpr_read_b32 v28, a92
	v_accvgpr_read_b32 v29, a93
	v_accvgpr_read_b32 v30, a94
	v_accvgpr_read_b32 v31, a95
	v_accvgpr_read_b32 v65, a97
	v_accvgpr_read_b32 v66, a98
	v_accvgpr_read_b32 v67, a99
	v_accvgpr_read_b32 v68, a100
	v_accvgpr_read_b32 v69, a101
	v_accvgpr_read_b32 v70, a102
	v_accvgpr_read_b32 v71, a103
	v_accvgpr_read_b32 v72, a104
	v_accvgpr_read_b32 v73, a105
	v_accvgpr_read_b32 v74, a106
	v_accvgpr_read_b32 v75, a107
	v_accvgpr_read_b32 v76, a108
	v_accvgpr_read_b32 v77, a109
	v_accvgpr_read_b32 v78, a110
	v_accvgpr_read_b32 v79, a111
	v_accvgpr_read_b32 v1, a33
	v_accvgpr_read_b32 v2, a34
	v_accvgpr_read_b32 v3, a35
	v_accvgpr_read_b32 v4, a36
	v_accvgpr_read_b32 v5, a37
	v_accvgpr_read_b32 v6, a38
	v_accvgpr_read_b32 v7, a39
	v_accvgpr_read_b32 v8, a40
	v_accvgpr_read_b32 v9, a41
	v_accvgpr_read_b32 v10, a42
	v_accvgpr_read_b32 v11, a43
	v_accvgpr_read_b32 v12, a44
	v_accvgpr_read_b32 v13, a45
	v_accvgpr_read_b32 v14, a46
	v_accvgpr_read_b32 v15, a47
	v_div_fixup_f32 v168, v130, v131, 1.0
	s_barrier
	s_and_saveexec_b64 s[60:61], s[6:7]
	s_cbranch_execz .LBB0_2274
	v_accvgpr_read_b32 v133, a216
	v_mul_f32_e32 v130, v133, v222
	v_mul_f32_e32 v131, v112, v130
	v_mul_f32_e32 v132, v113, v130
	ds_write2st64_b32 v139, v131, v132 offset1:1
	v_mul_f32_e32 v131, v114, v130
	v_mul_f32_e32 v132, v115, v130
	ds_write2st64_b32 v139, v131, v132 offset0:2 offset1:3
	v_mul_f32_e32 v131, v116, v130
	v_mul_f32_e32 v132, v117, v130
	ds_write2st64_b32 v139, v131, v132 offset0:4 offset1:5
	v_mul_f32_e32 v131, v118, v130
	v_mul_f32_e32 v132, v119, v130
	ds_write2st64_b32 v139, v131, v132 offset0:6 offset1:7
	v_mul_f32_e32 v131, v120, v130
	v_mul_f32_e32 v132, v121, v130
	ds_write2st64_b32 v139, v131, v132 offset0:8 offset1:9
	v_mul_f32_e32 v131, v122, v130
	v_mul_f32_e32 v132, v123, v130
	ds_write2st64_b32 v139, v131, v132 offset0:10 offset1:11
	v_mul_f32_e32 v131, v124, v130
	v_mul_f32_e32 v132, v125, v130
	ds_write2st64_b32 v139, v131, v132 offset0:12 offset1:13
	v_mul_f32_e32 v131, v126, v130
	v_mul_f32_e32 v132, v127, v130
	ds_write2st64_b32 v139, v131, v132 offset0:14 offset1:15
	v_mul_f32_e32 v131, v96, v130
	v_mul_f32_e32 v132, v97, v130
	ds_write2st64_b32 v139, v131, v132 offset0:16 offset1:17
	v_mul_f32_e32 v131, v98, v130
	v_mul_f32_e32 v132, v99, v130
	ds_write2st64_b32 v139, v131, v132 offset0:18 offset1:19
	v_mul_f32_e32 v131, v100, v130
	v_mul_f32_e32 v132, v101, v130
	ds_write2st64_b32 v139, v131, v132 offset0:20 offset1:21
	v_mul_f32_e32 v131, v102, v130
	v_mul_f32_e32 v132, v103, v130
	ds_write2st64_b32 v139, v131, v132 offset0:22 offset1:23
	v_mul_f32_e32 v131, v104, v130
	v_mul_f32_e32 v132, v105, v130
	ds_write2st64_b32 v139, v131, v132 offset0:24 offset1:25
	v_mul_f32_e32 v131, v106, v130
	v_mul_f32_e32 v132, v107, v130
	ds_write2st64_b32 v139, v131, v132 offset0:26 offset1:27
	v_mul_f32_e32 v131, v108, v130
	v_mul_f32_e32 v132, v109, v130
	ds_write2st64_b32 v139, v131, v132 offset0:28 offset1:29
	v_mul_f32_e32 v131, v110, v130
	v_mul_f32_e32 v132, v111, v130
	ds_write2st64_b32 v139, v131, v132 offset0:30 offset1:31
	v_mul_f32_e32 v131, v80, v130
	v_mul_f32_e32 v132, v81, v130
	ds_write2st64_b32 v139, v131, v132 offset0:32 offset1:33
	v_mul_f32_e32 v131, v82, v130
	v_mul_f32_e32 v132, v83, v130
	ds_write2st64_b32 v139, v131, v132 offset0:34 offset1:35
	v_mul_f32_e32 v131, v84, v130
	v_mul_f32_e32 v132, v85, v130
	ds_write2st64_b32 v139, v131, v132 offset0:36 offset1:37
	v_mul_f32_e32 v131, v86, v130
	v_mul_f32_e32 v132, v87, v130
	ds_write2st64_b32 v139, v131, v132 offset0:38 offset1:39
	v_mul_f32_e32 v131, v88, v130
	v_mul_f32_e32 v132, v89, v130
	ds_write2st64_b32 v139, v131, v132 offset0:40 offset1:41
	v_mul_f32_e32 v131, v90, v130
	v_mul_f32_e32 v132, v91, v130
	ds_write2st64_b32 v139, v131, v132 offset0:42 offset1:43
	v_mul_f32_e32 v131, v92, v130
	v_mul_f32_e32 v132, v93, v130
	ds_write2st64_b32 v139, v131, v132 offset0:44 offset1:45
	v_mul_f32_e32 v131, v94, v130
	v_mul_f32_e32 v132, v95, v130
	ds_write2st64_b32 v139, v131, v132 offset0:46 offset1:47
	v_mul_f32_e32 v131, v64, v130
	v_mul_f32_e32 v132, v65, v130
	ds_write2st64_b32 v139, v131, v132 offset0:48 offset1:49
	v_mul_f32_e32 v131, v66, v130
	v_mul_f32_e32 v132, v67, v130
	ds_write2st64_b32 v139, v131, v132 offset0:50 offset1:51
	v_mul_f32_e32 v131, v68, v130
	v_mul_f32_e32 v132, v69, v130
	ds_write2st64_b32 v139, v131, v132 offset0:52 offset1:53
	v_mul_f32_e32 v131, v70, v130
	v_mul_f32_e32 v132, v71, v130
	ds_write2st64_b32 v139, v131, v132 offset0:54 offset1:55
	v_mul_f32_e32 v131, v72, v130
	v_mul_f32_e32 v132, v73, v130
	ds_write2st64_b32 v139, v131, v132 offset0:56 offset1:57
	v_mul_f32_e32 v131, v74, v130
	v_mul_f32_e32 v132, v75, v130
	ds_write2st64_b32 v139, v131, v132 offset0:58 offset1:59
	v_mul_f32_e32 v131, v76, v130
	v_mul_f32_e32 v132, v77, v130
	ds_write2st64_b32 v139, v131, v132 offset0:60 offset1:61
	v_mul_f32_e32 v131, v78, v130
	v_mul_f32_e32 v130, v79, v130
	ds_write2st64_b32 v139, v131, v130 offset0:62 offset1:63
	v_mul_f32_e32 v130, v133, v168
	v_mul_f32_e32 v131, v48, v130
	v_mul_f32_e32 v132, v49, v130
	ds_write2st64_b32 v254, v131, v132 offset1:1
	v_mul_f32_e32 v131, v50, v130
	v_mul_f32_e32 v132, v51, v130
	ds_write2st64_b32 v254, v131, v132 offset0:2 offset1:3
	v_mul_f32_e32 v131, v52, v130
	v_mul_f32_e32 v132, v53, v130
	ds_write2st64_b32 v254, v131, v132 offset0:4 offset1:5
	v_mul_f32_e32 v131, v54, v130
	v_mul_f32_e32 v132, v55, v130
	ds_write2st64_b32 v254, v131, v132 offset0:6 offset1:7
	v_mul_f32_e32 v131, v56, v130
	v_mul_f32_e32 v132, v57, v130
	ds_write2st64_b32 v254, v131, v132 offset0:8 offset1:9
	v_mul_f32_e32 v131, v58, v130
	v_mul_f32_e32 v132, v59, v130
	ds_write2st64_b32 v254, v131, v132 offset0:10 offset1:11
	v_mul_f32_e32 v131, v60, v130
	v_mul_f32_e32 v132, v61, v130
	ds_write2st64_b32 v254, v131, v132 offset0:12 offset1:13
	v_mul_f32_e32 v131, v62, v130
	v_mul_f32_e32 v132, v63, v130
	ds_write2st64_b32 v254, v131, v132 offset0:14 offset1:15
	v_mul_f32_e32 v131, v32, v130
	v_mul_f32_e32 v132, v33, v130
	ds_write2st64_b32 v254, v131, v132 offset0:16 offset1:17
	v_mul_f32_e32 v131, v34, v130
	v_mul_f32_e32 v132, v35, v130
	ds_write2st64_b32 v254, v131, v132 offset0:18 offset1:19
	v_mul_f32_e32 v131, v36, v130
	v_mul_f32_e32 v132, v37, v130
	ds_write2st64_b32 v254, v131, v132 offset0:20 offset1:21
	v_mul_f32_e32 v131, v38, v130
	v_mul_f32_e32 v132, v39, v130
	ds_write2st64_b32 v254, v131, v132 offset0:22 offset1:23
	v_mul_f32_e32 v131, v40, v130
	v_mul_f32_e32 v132, v41, v130
	ds_write2st64_b32 v254, v131, v132 offset0:24 offset1:25
	v_mul_f32_e32 v131, v42, v130
	v_mul_f32_e32 v132, v43, v130
	ds_write2st64_b32 v254, v131, v132 offset0:26 offset1:27
	v_mul_f32_e32 v131, v44, v130
	v_mul_f32_e32 v132, v45, v130
	ds_write2st64_b32 v254, v131, v132 offset0:28 offset1:29
	v_mul_f32_e32 v131, v46, v130
	v_mul_f32_e32 v132, v47, v130
	ds_write2st64_b32 v254, v131, v132 offset0:30 offset1:31
	v_mul_f32_e32 v131, v16, v130
	v_mul_f32_e32 v132, v17, v130
	ds_write2st64_b32 v254, v131, v132 offset0:32 offset1:33
	v_mul_f32_e32 v131, v18, v130
	v_mul_f32_e32 v132, v19, v130
	ds_write2st64_b32 v254, v131, v132 offset0:34 offset1:35
	v_mul_f32_e32 v131, v20, v130
	v_mul_f32_e32 v132, v21, v130
	ds_write2st64_b32 v254, v131, v132 offset0:36 offset1:37
	v_mul_f32_e32 v131, v22, v130
	v_mul_f32_e32 v132, v23, v130
	ds_write2st64_b32 v254, v131, v132 offset0:38 offset1:39
	v_mul_f32_e32 v131, v24, v130
	v_mul_f32_e32 v132, v25, v130
	ds_write2st64_b32 v254, v131, v132 offset0:40 offset1:41
	v_mul_f32_e32 v131, v26, v130
	v_mul_f32_e32 v132, v27, v130
	ds_write2st64_b32 v254, v131, v132 offset0:42 offset1:43
	v_mul_f32_e32 v131, v28, v130
	v_mul_f32_e32 v132, v29, v130
	ds_write2st64_b32 v254, v131, v132 offset0:44 offset1:45
	v_mul_f32_e32 v131, v30, v130
	v_mul_f32_e32 v132, v31, v130
	ds_write2st64_b32 v254, v131, v132 offset0:46 offset1:47
	v_mul_f32_e32 v131, v0, v130
	v_mul_f32_e32 v132, v1, v130
	ds_write2st64_b32 v254, v131, v132 offset0:48 offset1:49
	v_mul_f32_e32 v131, v2, v130
	v_mul_f32_e32 v132, v3, v130
	ds_write2st64_b32 v254, v131, v132 offset0:50 offset1:51
	v_mul_f32_e32 v131, v4, v130
	v_mul_f32_e32 v132, v5, v130
	ds_write2st64_b32 v254, v131, v132 offset0:52 offset1:53
	v_mul_f32_e32 v131, v6, v130
	v_mul_f32_e32 v132, v7, v130
	ds_write2st64_b32 v254, v131, v132 offset0:54 offset1:55
	v_mul_f32_e32 v131, v8, v130
	v_mul_f32_e32 v132, v9, v130
	ds_write2st64_b32 v254, v131, v132 offset0:56 offset1:57
	v_mul_f32_e32 v131, v10, v130
	v_mul_f32_e32 v132, v11, v130
	ds_write2st64_b32 v254, v131, v132 offset0:58 offset1:59
	v_mul_f32_e32 v131, v12, v130
	v_mul_f32_e32 v132, v13, v130
	ds_write2st64_b32 v254, v131, v132 offset0:60 offset1:61
	v_mul_f32_e32 v131, v14, v130
	v_mul_f32_e32 v130, v15, v130
	ds_write2st64_b32 v254, v131, v130 offset0:62 offset1:63
